# code placement: the 13 GEMM K-loop heads aligned to 64 bytes (.p2align 6, s_nop padding executed once per tile)
# speedup vs baseline: 1.0029x; 1.0029x over previous
; template <class Epi, class Map>
; __device__ __forceinline__ void gemm_phase(LAS unsigned char* lds, const Gemm g, const Sched<Map>& S, const Epi& E) {
;     ...
;         const char* nA = has_next ? (const char*)g.A + nxt.aoff : cA; const char* nB = has_next ? (const char*)g.Bt + nxt.boff : cB;
; #pragma unroll 1
;         for (int t = 0; t < nt; t += 2) {
;             const bool last = (t == nt - 2);
;             const char* a1 = cA + (size_t)(t + 1) * kstep;
;             const char* a2 = last ? nA : cA + (size_t)(t + 2) * kstep; const char* b2 = last ? nB : cB + (size_t)(t + 2) * kstep;
;             const char* a3 = a2 + kstep; const char* b3 = b2 + kstep;
;     ...
; #pragma unroll
;         for (int a = 0; a < 2; ++a)
; #pragma unroll
;             for (int b = 0; b < 2; ++b)
; #pragma unroll
;                 for (int m = 0; m < 4; ++m)
; #pragma unroll
;                     for (int n = 0; n < 2; ++n) acc[a][b][m][n] = (f32x4){0.f, 0.f, 0.f, 0.f};
;         cur = nxt; cA = nA; cB = nB; ++ui;
.LBB0_222:
	s_add_u32 s34, s16, s54
	s_addc_u32 s35, s17, 0
	s_and_b64 s[36:37], s[40:41], exec
	s_cselect_b32 s56, s35, s43
	s_cselect_b32 s57, s34, s42
	s_add_u32 s36, s3, s53
	s_addc_u32 s37, s4, 0
	s_and_b64 s[48:49], s[40:41], exec
	s_cselect_b32 s58, s37, s47
	s_cselect_b32 s59, s36, s46
	s_add_u32 s48, s42, 0x80
	s_addc_u32 s49, s43, 0
	s_add_u32 s65, s46, 0x100
	v_mov_b32_e32 v0, 0
	v_lshl_add_u64 v[128:129], s[48:49], 0, v[158:159]
	v_lshl_add_u64 v[130:131], s[48:49], 0, v[160:161]
	s_addc_u32 s66, s47, 0
	s_mov_b32 s67, -2
	s_mov_b64 s[46:47], 0
	v_mov_b32_e32 v1, v0
	v_mov_b32_e32 v2, v0
	v_mov_b32_e32 v3, v0
	v_mov_b32_e32 v4, v0
	v_mov_b32_e32 v5, v0
	v_mov_b32_e32 v6, v0
	v_mov_b32_e32 v7, v0
	s_waitcnt vmcnt(0)
	v_mov_b32_e32 v16, v0
	v_mov_b32_e32 v17, v0
	v_mov_b32_e32 v18, v0
	v_mov_b32_e32 v19, v0
	v_mov_b32_e32 v20, v0
	v_mov_b32_e32 v21, v0
	v_mov_b32_e32 v22, v0
	v_mov_b32_e32 v23, v0
	v_mov_b32_e32 v32, v0
	v_mov_b32_e32 v33, v0
	v_mov_b32_e32 v34, v0
	v_mov_b32_e32 v35, v0
	v_mov_b32_e32 v36, v0
	v_mov_b32_e32 v37, v0
	v_mov_b32_e32 v38, v0
	v_mov_b32_e32 v39, v0
	v_mov_b32_e32 v48, v0
	v_mov_b32_e32 v49, v0
	v_mov_b32_e32 v50, v0
	v_mov_b32_e32 v51, v0
	v_mov_b32_e32 v52, v0
	v_mov_b32_e32 v53, v0
	v_mov_b32_e32 v54, v0
	v_mov_b32_e32 v55, v0
	v_mov_b32_e32 v8, v0
	v_mov_b32_e32 v9, v0
	v_mov_b32_e32 v10, v0
	v_mov_b32_e32 v11, v0
	v_mov_b32_e32 v12, v0
	v_mov_b32_e32 v13, v0
	v_mov_b32_e32 v14, v0
	v_mov_b32_e32 v15, v0
	v_mov_b32_e32 v24, v0
	v_mov_b32_e32 v25, v0
	v_mov_b32_e32 v26, v0
	v_mov_b32_e32 v27, v0
	v_mov_b32_e32 v28, v0
	v_mov_b32_e32 v29, v0
	v_mov_b32_e32 v30, v0
	v_mov_b32_e32 v31, v0
	v_mov_b32_e32 v40, v0
	v_mov_b32_e32 v41, v0
	v_mov_b32_e32 v42, v0
	v_mov_b32_e32 v43, v0
	v_mov_b32_e32 v44, v0
	v_mov_b32_e32 v45, v0
	v_mov_b32_e32 v46, v0
	v_mov_b32_e32 v47, v0
	v_mov_b32_e32 v56, v0
	v_mov_b32_e32 v57, v0
	v_mov_b32_e32 v58, v0
	v_mov_b32_e32 v59, v0
	v_mov_b32_e32 v60, v0
	v_mov_b32_e32 v61, v0
	v_mov_b32_e32 v62, v0
	v_mov_b32_e32 v63, v0
	v_mov_b32_e32 v64, v0
	v_mov_b32_e32 v65, v0
	v_mov_b32_e32 v66, v0
	v_mov_b32_e32 v67, v0
	v_mov_b32_e32 v68, v0
	v_mov_b32_e32 v69, v0
	v_mov_b32_e32 v70, v0
	v_mov_b32_e32 v71, v0
	v_mov_b32_e32 v80, v0
	v_mov_b32_e32 v81, v0
	v_mov_b32_e32 v82, v0
	v_mov_b32_e32 v83, v0
	v_mov_b32_e32 v84, v0
	v_mov_b32_e32 v85, v0
	v_mov_b32_e32 v86, v0
	v_mov_b32_e32 v87, v0
	v_mov_b32_e32 v96, v0
	v_mov_b32_e32 v97, v0
	v_mov_b32_e32 v98, v0
	v_mov_b32_e32 v99, v0
	v_mov_b32_e32 v100, v0
	v_mov_b32_e32 v101, v0
	v_mov_b32_e32 v102, v0
	v_mov_b32_e32 v103, v0
	v_mov_b32_e32 v112, v0
	v_mov_b32_e32 v113, v0
	v_mov_b32_e32 v114, v0
	v_mov_b32_e32 v115, v0
	v_mov_b32_e32 v116, v0
	v_mov_b32_e32 v117, v0
	v_mov_b32_e32 v118, v0
	v_mov_b32_e32 v119, v0
	v_mov_b32_e32 v72, v0
	v_mov_b32_e32 v73, v0
	v_mov_b32_e32 v74, v0
	v_mov_b32_e32 v75, v0
	v_mov_b32_e32 v76, v0
	v_mov_b32_e32 v77, v0
	v_mov_b32_e32 v78, v0
	v_mov_b32_e32 v79, v0
	v_mov_b32_e32 v88, v0
	v_mov_b32_e32 v89, v0
	v_mov_b32_e32 v90, v0
	v_mov_b32_e32 v91, v0
	v_mov_b32_e32 v92, v0
	v_mov_b32_e32 v93, v0
	v_mov_b32_e32 v94, v0
	v_mov_b32_e32 v95, v0
	v_mov_b32_e32 v104, v0
	v_mov_b32_e32 v105, v0
	v_mov_b32_e32 v106, v0
	v_mov_b32_e32 v107, v0
	v_mov_b32_e32 v108, v0
	v_mov_b32_e32 v109, v0
	v_mov_b32_e32 v110, v0
	v_mov_b32_e32 v111, v0
	v_mov_b32_e32 v120, v0
	v_mov_b32_e32 v121, v0
	v_mov_b32_e32 v122, v0
	v_mov_b32_e32 v123, v0
	v_mov_b32_e32 v124, v0
	v_mov_b32_e32 v125, v0
	v_mov_b32_e32 v126, v0
	v_mov_b32_e32 v127, v0
	.p2align 6

; template <class Epi, class Map>
; __device__ __forceinline__ void gemm_phase(LAS unsigned char* lds, const Gemm g, const Sched<Map>& S, const Epi& E) {
;     ...
;         const char* nA = has_next ? (const char*)g.A + nxt.aoff : cA; const char* nB = has_next ? (const char*)g.Bt + nxt.boff : cB;
; #pragma unroll 1
;         for (int t = 0; t < nt; t += 2) {
;             const bool last = (t == nt - 2);
;             const char* a1 = cA + (size_t)(t + 1) * kstep;
;             const char* a2 = last ? nA : cA + (size_t)(t + 2) * kstep; const char* b2 = last ? nB : cB + (size_t)(t + 2) * kstep;
;             const char* a3 = a2 + kstep; const char* b3 = b2 + kstep;
;     ...
; #pragma unroll
;         for (int a = 0; a < 2; ++a)
; #pragma unroll
;             for (int b = 0; b < 2; ++b)
; #pragma unroll
;                 for (int m = 0; m < 4; ++m)
; #pragma unroll
;                     for (int n = 0; n < 2; ++n) acc[a][b][m][n] = (f32x4){0.f, 0.f, 0.f, 0.f};
;         cur = nxt; cA = nA; cB = nB; ++ui;
.LBB0_260:
	s_add_u32 s28, s2, s43
	s_addc_u32 s29, s3, 0
	s_and_b64 s[30:31], s[40:41], exec
	s_cselect_b32 s25, s29, s35
	s_cselect_b32 s46, s28, s34
	s_add_u32 s30, s16, s44
	s_addc_u32 s31, s17, 0
	s_and_b64 s[48:49], s[40:41], exec
	s_cselect_b32 s47, s31, s37
	s_cselect_b32 s48, s30, s36
	s_add_u32 s34, s34, 0x80080
	s_addc_u32 s35, s35, 0
	s_add_u32 s49, s36, 0x100
	v_mov_b32_e32 v0, 0
	s_addc_u32 s50, s37, 0
	s_mov_b32 s51, -2
	v_mov_b32_e32 v1, v0
	v_mov_b32_e32 v2, v0
	v_mov_b32_e32 v3, v0
	v_mov_b32_e32 v4, v0
	v_mov_b32_e32 v5, v0
	v_mov_b32_e32 v6, v0
	v_mov_b32_e32 v7, v0
	v_mov_b32_e32 v8, v0
	v_mov_b32_e32 v9, v0
	v_mov_b32_e32 v10, v0
	v_mov_b32_e32 v11, v0
	v_mov_b32_e32 v16, v0
	v_mov_b32_e32 v17, v0
	v_mov_b32_e32 v18, v0
	v_mov_b32_e32 v19, v0
	v_mov_b32_e32 v24, v0
	v_mov_b32_e32 v25, v0
	v_mov_b32_e32 v26, v0
	v_mov_b32_e32 v27, v0
	v_mov_b32_e32 v32, v0
	v_mov_b32_e32 v33, v0
	v_mov_b32_e32 v34, v0
	v_mov_b32_e32 v35, v0
	v_mov_b32_e32 v40, v0
	v_mov_b32_e32 v41, v0
	v_mov_b32_e32 v42, v0
	v_mov_b32_e32 v43, v0
	v_mov_b32_e32 v48, v0
	v_mov_b32_e32 v49, v0
	v_mov_b32_e32 v50, v0
	v_mov_b32_e32 v51, v0
	v_mov_b32_e32 v12, v0
	v_mov_b32_e32 v13, v0
	v_mov_b32_e32 v14, v0
	v_mov_b32_e32 v15, v0
	v_mov_b32_e32 v20, v0
	v_mov_b32_e32 v21, v0
	v_mov_b32_e32 v22, v0
	v_mov_b32_e32 v23, v0
	v_mov_b32_e32 v28, v0
	v_mov_b32_e32 v29, v0
	v_mov_b32_e32 v30, v0
	v_mov_b32_e32 v31, v0
	v_mov_b32_e32 v36, v0
	v_mov_b32_e32 v37, v0
	v_mov_b32_e32 v38, v0
	v_mov_b32_e32 v39, v0
	v_mov_b32_e32 v44, v0
	v_mov_b32_e32 v45, v0
	v_mov_b32_e32 v46, v0
	v_mov_b32_e32 v47, v0
	v_mov_b32_e32 v52, v0
	v_mov_b32_e32 v53, v0
	v_mov_b32_e32 v54, v0
	v_mov_b32_e32 v55, v0
	v_mov_b32_e32 v56, v0
	v_mov_b32_e32 v57, v0
	v_mov_b32_e32 v58, v0
	v_mov_b32_e32 v59, v0
	v_mov_b32_e32 v60, v0
	v_mov_b32_e32 v61, v0
	v_mov_b32_e32 v62, v0
	v_mov_b32_e32 v63, v0
	v_mov_b32_e32 v64, v0
	v_mov_b32_e32 v65, v0
	v_mov_b32_e32 v66, v0
	v_mov_b32_e32 v67, v0
	v_mov_b32_e32 v68, v0
	v_mov_b32_e32 v69, v0
	v_mov_b32_e32 v70, v0
	v_mov_b32_e32 v71, v0
	v_mov_b32_e32 v72, v0
	v_mov_b32_e32 v73, v0
	v_mov_b32_e32 v74, v0
	v_mov_b32_e32 v75, v0
	v_mov_b32_e32 v80, v0
	v_mov_b32_e32 v81, v0
	v_mov_b32_e32 v82, v0
	v_mov_b32_e32 v83, v0
	v_mov_b32_e32 v88, v0
	v_mov_b32_e32 v89, v0
	v_mov_b32_e32 v90, v0
	v_mov_b32_e32 v91, v0
	v_mov_b32_e32 v96, v0
	v_mov_b32_e32 v97, v0
	v_mov_b32_e32 v98, v0
	v_mov_b32_e32 v99, v0
	v_mov_b32_e32 v104, v0
	v_mov_b32_e32 v105, v0
	v_mov_b32_e32 v106, v0
	v_mov_b32_e32 v107, v0
	v_mov_b32_e32 v112, v0
	v_mov_b32_e32 v113, v0
	v_mov_b32_e32 v114, v0
	v_mov_b32_e32 v115, v0
	v_mov_b32_e32 v76, v0
	v_mov_b32_e32 v77, v0
	v_mov_b32_e32 v78, v0
	v_mov_b32_e32 v79, v0
	v_mov_b32_e32 v84, v0
	v_mov_b32_e32 v85, v0
	v_mov_b32_e32 v86, v0
	v_mov_b32_e32 v87, v0
	v_mov_b32_e32 v92, v0
	v_mov_b32_e32 v93, v0
	v_mov_b32_e32 v94, v0
	v_mov_b32_e32 v95, v0
	v_mov_b32_e32 v100, v0
	v_mov_b32_e32 v101, v0
	v_mov_b32_e32 v102, v0
	v_mov_b32_e32 v103, v0
	v_mov_b32_e32 v108, v0
	v_mov_b32_e32 v109, v0
	v_mov_b32_e32 v110, v0
	v_mov_b32_e32 v111, v0
	v_mov_b32_e32 v116, v0
	v_mov_b32_e32 v117, v0
	v_mov_b32_e32 v118, v0
	v_mov_b32_e32 v119, v0
	v_mov_b32_e32 v120, v0
	v_mov_b32_e32 v121, v0
	v_mov_b32_e32 v122, v0
	v_mov_b32_e32 v123, v0
	v_mov_b32_e32 v124, v0
	v_mov_b32_e32 v125, v0
	v_mov_b32_e32 v126, v0
	v_mov_b32_e32 v127, v0
	.p2align 6

; template <class Epi, class Map>
; __device__ __forceinline__ void gemm_phase(LAS unsigned char* lds, const Gemm g, const Sched<Map>& S, const Epi& E) {
;     ...
;         const char* nA = has_next ? (const char*)g.A + nxt.aoff : cA; const char* nB = has_next ? (const char*)g.Bt + nxt.boff : cB;
; #pragma unroll 1
;         for (int t = 0; t < nt; t += 2) {
;             const bool last = (t == nt - 2);
;             const char* a1 = cA + (size_t)(t + 1) * kstep;
;             const char* a2 = last ? nA : cA + (size_t)(t + 2) * kstep; const char* b2 = last ? nB : cB + (size_t)(t + 2) * kstep;
;             const char* a3 = a2 + kstep; const char* b3 = b2 + kstep;
;     ...
; #pragma unroll
;         for (int a = 0; a < 2; ++a)
; #pragma unroll
;             for (int b = 0; b < 2; ++b)
; #pragma unroll
;                 for (int m = 0; m < 4; ++m)
; #pragma unroll
;                     for (int n = 0; n < 2; ++n) acc[a][b][m][n] = (f32x4){0.f, 0.f, 0.f, 0.f};
;         cur = nxt; cA = nA; cB = nB; ++ui;
.LBB0_404:
	v_readlane_b32 s20, v245, 21
	v_readlane_b32 s21, v245, 22
	s_add_u32 s20, s20, s33
	s_addc_u32 s21, s21, 0
	s_and_b64 s[24:25], s[38:39], exec
	v_readlane_b32 s5, v247, 56
	s_cselect_b32 s40, s21, s29
	s_cselect_b32 s41, s20, s28
	s_add_u32 s24, s5, s15
	v_readlane_b32 s5, v247, 57
	s_addc_u32 s25, s5, 0
	s_and_b64 s[34:35], s[38:39], exec
	s_cselect_b32 s42, s25, s31
	s_cselect_b32 s43, s24, s30
	s_add_u32 s28, s28, 0x80080
	s_addc_u32 s29, s29, 0
	s_add_u32 s44, s30, 0x100
	v_mov_b32_e32 v0, 0
	s_addc_u32 s45, s31, 0
	s_mov_b32 s46, -2
	v_mov_b32_e32 v1, v0
	v_mov_b32_e32 v2, v0
	v_mov_b32_e32 v3, v0
	v_mov_b32_e32 v4, v0
	v_mov_b32_e32 v5, v0
	v_mov_b32_e32 v6, v0
	v_mov_b32_e32 v7, v0
	v_mov_b32_e32 v12, v0
	v_mov_b32_e32 v13, v0
	v_mov_b32_e32 v14, v0
	v_mov_b32_e32 v15, v0
	v_mov_b32_e32 v16, v0
	v_mov_b32_e32 v17, v0
	v_mov_b32_e32 v18, v0
	v_mov_b32_e32 v19, v0
	v_mov_b32_e32 v32, v0
	v_mov_b32_e32 v33, v0
	v_mov_b32_e32 v34, v0
	v_mov_b32_e32 v35, v0
	v_mov_b32_e32 v36, v0
	v_mov_b32_e32 v37, v0
	v_mov_b32_e32 v38, v0
	v_mov_b32_e32 v39, v0
	v_mov_b32_e32 v40, v0
	v_mov_b32_e32 v41, v0
	v_mov_b32_e32 v42, v0
	v_mov_b32_e32 v43, v0
	v_mov_b32_e32 v44, v0
	v_mov_b32_e32 v45, v0
	v_mov_b32_e32 v46, v0
	v_mov_b32_e32 v47, v0
	v_mov_b32_e32 v8, v0
	v_mov_b32_e32 v9, v0
	v_mov_b32_e32 v10, v0
	v_mov_b32_e32 v11, v0
	v_mov_b32_e32 v20, v0
	v_mov_b32_e32 v21, v0
	v_mov_b32_e32 v22, v0
	v_mov_b32_e32 v23, v0
	v_mov_b32_e32 v24, v0
	v_mov_b32_e32 v25, v0
	v_mov_b32_e32 v26, v0
	v_mov_b32_e32 v27, v0
	v_mov_b32_e32 v28, v0
	v_mov_b32_e32 v29, v0
	v_mov_b32_e32 v30, v0
	v_mov_b32_e32 v31, v0
	v_mov_b32_e32 v48, v0
	v_mov_b32_e32 v49, v0
	v_mov_b32_e32 v50, v0
	v_mov_b32_e32 v51, v0
	v_mov_b32_e32 v52, v0
	v_mov_b32_e32 v53, v0
	v_mov_b32_e32 v54, v0
	v_mov_b32_e32 v55, v0
	v_mov_b32_e32 v56, v0
	v_mov_b32_e32 v57, v0
	v_mov_b32_e32 v58, v0
	v_mov_b32_e32 v59, v0
	v_mov_b32_e32 v60, v0
	v_mov_b32_e32 v61, v0
	v_mov_b32_e32 v62, v0
	v_mov_b32_e32 v63, v0
	v_mov_b32_e32 v76, v0
	v_mov_b32_e32 v77, v0
	v_mov_b32_e32 v78, v0
	v_mov_b32_e32 v79, v0
	v_mov_b32_e32 v80, v0
	v_mov_b32_e32 v81, v0
	v_mov_b32_e32 v82, v0
	v_mov_b32_e32 v83, v0
	v_mov_b32_e32 v84, v0
	v_mov_b32_e32 v85, v0
	v_mov_b32_e32 v86, v0
	v_mov_b32_e32 v87, v0
	v_mov_b32_e32 v88, v0
	v_mov_b32_e32 v89, v0
	v_mov_b32_e32 v90, v0
	v_mov_b32_e32 v91, v0
	v_mov_b32_e32 v112, v0
	v_mov_b32_e32 v113, v0
	v_mov_b32_e32 v114, v0
	v_mov_b32_e32 v115, v0
	v_mov_b32_e32 v116, v0
	v_mov_b32_e32 v117, v0
	v_mov_b32_e32 v118, v0
	v_mov_b32_e32 v119, v0
	v_mov_b32_e32 v120, v0
	v_mov_b32_e32 v121, v0
	v_mov_b32_e32 v122, v0
	v_mov_b32_e32 v123, v0
	v_mov_b32_e32 v124, v0
	v_mov_b32_e32 v125, v0
	v_mov_b32_e32 v126, v0
	v_mov_b32_e32 v127, v0
	v_mov_b32_e32 v92, v0
	v_mov_b32_e32 v93, v0
	v_mov_b32_e32 v94, v0
	v_mov_b32_e32 v95, v0
	v_mov_b32_e32 v96, v0
	v_mov_b32_e32 v97, v0
	v_mov_b32_e32 v98, v0
	v_mov_b32_e32 v99, v0
	v_mov_b32_e32 v100, v0
	v_mov_b32_e32 v101, v0
	v_mov_b32_e32 v102, v0
	v_mov_b32_e32 v103, v0
	v_mov_b32_e32 v104, v0
	v_mov_b32_e32 v105, v0
	v_mov_b32_e32 v106, v0
	v_mov_b32_e32 v107, v0
	v_mov_b32_e32 v128, v0
	v_mov_b32_e32 v129, v0
	v_mov_b32_e32 v130, v0
	v_mov_b32_e32 v131, v0
	v_mov_b32_e32 v132, v0
	v_mov_b32_e32 v133, v0
	v_mov_b32_e32 v134, v0
	v_mov_b32_e32 v135, v0
	v_mov_b32_e32 v136, v0
	v_mov_b32_e32 v137, v0
	v_mov_b32_e32 v138, v0
	v_mov_b32_e32 v139, v0
	v_mov_b32_e32 v140, v0
	v_mov_b32_e32 v141, v0
	v_mov_b32_e32 v142, v0
	v_mov_b32_e32 v143, v0
	.p2align 6

; template <class Epi, class Map>
; __device__ __forceinline__ void gemm_phase(LAS unsigned char* lds, const Gemm g, const Sched<Map>& S, const Epi& E) {
;     ...
;         const char* nA = has_next ? (const char*)g.A + nxt.aoff : cA; const char* nB = has_next ? (const char*)g.Bt + nxt.boff : cB;
; #pragma unroll 1
;         for (int t = 0; t < nt; t += 2) {
;             const bool last = (t == nt - 2);
;             const char* a1 = cA + (size_t)(t + 1) * kstep;
;             const char* a2 = last ? nA : cA + (size_t)(t + 2) * kstep; const char* b2 = last ? nB : cB + (size_t)(t + 2) * kstep;
;             const char* a3 = a2 + kstep; const char* b3 = b2 + kstep;
;     ...
; #pragma unroll
;         for (int a = 0; a < 2; ++a)
; #pragma unroll
;             for (int b = 0; b < 2; ++b)
; #pragma unroll
;                 for (int m = 0; m < 4; ++m)
; #pragma unroll
;                     for (int n = 0; n < 2; ++n) acc[a][b][m][n] = (f32x4){0.f, 0.f, 0.f, 0.f};
;         cur = nxt; cA = nA; cB = nB; ++ui;
.LBB0_551:
	s_add_u32 s54, s78, s6
	s_addc_u32 s55, s79, 0
	s_and_b64 s[8:9], s[40:41], exec
	s_cselect_b32 s3, s55, s25
	s_cselect_b32 s8, s54, s24
	s_add_u32 s58, s4, s1
	s_addc_u32 s59, s5, 0
	s_and_b64 s[10:11], s[40:41], exec
	s_cselect_b32 s9, s59, s29
	s_cselect_b32 s10, s58, s28
	s_add_u32 s24, s24, 0x80080
	s_addc_u32 s25, s25, 0
	s_add_u32 s11, s28, 0x100
	v_mov_b32_e32 v4, 0
	s_addc_u32 s12, s29, 0
	s_mov_b32 s13, -2
	v_mov_b32_e32 v5, v4
	v_mov_b32_e32 v6, v4
	v_mov_b32_e32 v7, v4
	v_mov_b32_e32 v8, v4
	v_mov_b32_e32 v9, v4
	v_mov_b32_e32 v10, v4
	v_mov_b32_e32 v11, v4
	v_mov_b32_e32 v20, v4
	v_mov_b32_e32 v21, v4
	v_mov_b32_e32 v22, v4
	v_mov_b32_e32 v23, v4
	v_mov_b32_e32 v24, v4
	v_mov_b32_e32 v25, v4
	v_mov_b32_e32 v26, v4
	v_mov_b32_e32 v27, v4
	v_mov_b32_e32 v36, v4
	v_mov_b32_e32 v37, v4
	v_mov_b32_e32 v38, v4
	v_mov_b32_e32 v39, v4
	v_mov_b32_e32 v40, v4
	v_mov_b32_e32 v41, v4
	v_mov_b32_e32 v42, v4
	v_mov_b32_e32 v43, v4
	v_mov_b32_e32 v52, v4
	v_mov_b32_e32 v53, v4
	v_mov_b32_e32 v54, v4
	v_mov_b32_e32 v55, v4
	v_mov_b32_e32 v56, v4
	v_mov_b32_e32 v57, v4
	v_mov_b32_e32 v58, v4
	v_mov_b32_e32 v59, v4
	v_mov_b32_e32 v0, v4
	v_mov_b32_e32 v1, v4
	v_mov_b32_e32 v2, v4
	v_mov_b32_e32 v3, v4
	v_mov_b32_e32 v12, v4
	v_mov_b32_e32 v13, v4
	v_mov_b32_e32 v14, v4
	v_mov_b32_e32 v15, v4
	v_mov_b32_e32 v16, v4
	v_mov_b32_e32 v17, v4
	v_mov_b32_e32 v18, v4
	v_mov_b32_e32 v19, v4
	v_mov_b32_e32 v28, v4
	v_mov_b32_e32 v29, v4
	v_mov_b32_e32 v30, v4
	v_mov_b32_e32 v31, v4
	v_mov_b32_e32 v32, v4
	v_mov_b32_e32 v33, v4
	v_mov_b32_e32 v34, v4
	v_mov_b32_e32 v35, v4
	v_mov_b32_e32 v44, v4
	v_mov_b32_e32 v45, v4
	v_mov_b32_e32 v46, v4
	v_mov_b32_e32 v47, v4
	v_mov_b32_e32 v48, v4
	v_mov_b32_e32 v49, v4
	v_mov_b32_e32 v50, v4
	v_mov_b32_e32 v51, v4
	v_mov_b32_e32 v60, v4
	v_mov_b32_e32 v61, v4
	v_mov_b32_e32 v62, v4
	v_mov_b32_e32 v63, v4
	v_mov_b32_e32 v68, v4
	v_mov_b32_e32 v69, v4
	v_mov_b32_e32 v70, v4
	v_mov_b32_e32 v71, v4
	v_mov_b32_e32 v72, v4
	v_mov_b32_e32 v73, v4
	v_mov_b32_e32 v74, v4
	v_mov_b32_e32 v75, v4
	v_mov_b32_e32 v84, v4
	v_mov_b32_e32 v85, v4
	v_mov_b32_e32 v86, v4
	v_mov_b32_e32 v87, v4
	v_mov_b32_e32 v88, v4
	v_mov_b32_e32 v89, v4
	v_mov_b32_e32 v90, v4
	v_mov_b32_e32 v91, v4
	v_mov_b32_e32 v100, v4
	v_mov_b32_e32 v101, v4
	v_mov_b32_e32 v102, v4
	v_mov_b32_e32 v103, v4
	v_mov_b32_e32 v104, v4
	v_mov_b32_e32 v105, v4
	v_mov_b32_e32 v106, v4
	v_mov_b32_e32 v107, v4
	v_mov_b32_e32 v112, v4
	v_mov_b32_e32 v113, v4
	v_mov_b32_e32 v114, v4
	v_mov_b32_e32 v115, v4
	v_mov_b32_e32 v120, v4
	v_mov_b32_e32 v121, v4
	v_mov_b32_e32 v122, v4
	v_mov_b32_e32 v123, v4
	v_mov_b32_e32 v64, v4
	v_mov_b32_e32 v65, v4
	v_mov_b32_e32 v66, v4
	v_mov_b32_e32 v67, v4
	v_mov_b32_e32 v76, v4
	v_mov_b32_e32 v77, v4
	v_mov_b32_e32 v78, v4
	v_mov_b32_e32 v79, v4
	v_mov_b32_e32 v80, v4
	v_mov_b32_e32 v81, v4
	v_mov_b32_e32 v82, v4
	v_mov_b32_e32 v83, v4
	v_mov_b32_e32 v92, v4
	v_mov_b32_e32 v93, v4
	v_mov_b32_e32 v94, v4
	v_mov_b32_e32 v95, v4
	v_mov_b32_e32 v96, v4
	v_mov_b32_e32 v97, v4
	v_mov_b32_e32 v98, v4
	v_mov_b32_e32 v99, v4
	v_mov_b32_e32 v108, v4
	v_mov_b32_e32 v109, v4
	v_mov_b32_e32 v110, v4
	v_mov_b32_e32 v111, v4
	v_mov_b32_e32 v116, v4
	v_mov_b32_e32 v117, v4
	v_mov_b32_e32 v118, v4
	v_mov_b32_e32 v119, v4
	v_mov_b32_e32 v124, v4
	v_mov_b32_e32 v125, v4
	v_mov_b32_e32 v126, v4
	v_mov_b32_e32 v127, v4
	.p2align 6

; template <class Epi, class Map>
; __device__ __forceinline__ void gemm_phase(LAS unsigned char* lds, const Gemm g, const Sched<Map>& S, const Epi& E) {
;     ...
;         const char* nA = has_next ? (const char*)g.A + nxt.aoff : cA; const char* nB = has_next ? (const char*)g.Bt + nxt.boff : cB;
; #pragma unroll 1
;         for (int t = 0; t < nt; t += 2) {
;             const bool last = (t == nt - 2);
;             const char* a1 = cA + (size_t)(t + 1) * kstep;
;             const char* a2 = last ? nA : cA + (size_t)(t + 2) * kstep; const char* b2 = last ? nB : cB + (size_t)(t + 2) * kstep;
;             const char* a3 = a2 + kstep; const char* b3 = b2 + kstep;
;     ...
; #pragma unroll
;         for (int a = 0; a < 2; ++a)
; #pragma unroll
;             for (int b = 0; b < 2; ++b)
; #pragma unroll
;                 for (int m = 0; m < 4; ++m)
; #pragma unroll
;                     for (int n = 0; n < 2; ++n) acc[a][b][m][n] = (f32x4){0.f, 0.f, 0.f, 0.f};
;         cur = nxt; cA = nA; cB = nB; ++ui;
.LBB0_586:
	v_readlane_b32 s12, v246, 9
	s_add_u32 s24, s12, s10
	v_readlane_b32 s12, v246, 10
	s_addc_u32 s25, s12, 0
	s_and_b64 s[12:13], s[42:43], exec
	s_cselect_b32 s12, s25, s31
	s_cselect_b32 s13, s24, s30
	s_add_u32 s28, s78, s9
	s_addc_u32 s29, s79, 0
	s_and_b64 s[14:15], s[42:43], exec
	s_cselect_b32 s14, s29, s35
	s_cselect_b32 s15, s28, s34
	s_add_u32 s30, s30, 0x80080
	s_addc_u32 s31, s31, 0
	s_add_u32 s21, s34, 0x100
	v_mov_b32_e32 v0, 0
	s_addc_u32 s33, s35, 0
	s_mov_b32 s38, -2
	v_mov_b32_e32 v1, v0
	v_mov_b32_e32 v2, v0
	v_mov_b32_e32 v3, v0
	v_mov_b32_e32 v4, v0
	v_mov_b32_e32 v5, v0
	v_mov_b32_e32 v6, v0
	v_mov_b32_e32 v7, v0
	v_mov_b32_e32 v8, v0
	v_mov_b32_e32 v9, v0
	v_mov_b32_e32 v10, v0
	v_mov_b32_e32 v11, v0
	v_mov_b32_e32 v16, v0
	v_mov_b32_e32 v17, v0
	v_mov_b32_e32 v18, v0
	v_mov_b32_e32 v19, v0
	v_mov_b32_e32 v24, v0
	v_mov_b32_e32 v25, v0
	v_mov_b32_e32 v26, v0
	v_mov_b32_e32 v27, v0
	v_mov_b32_e32 v32, v0
	v_mov_b32_e32 v33, v0
	v_mov_b32_e32 v34, v0
	v_mov_b32_e32 v35, v0
	v_mov_b32_e32 v40, v0
	v_mov_b32_e32 v41, v0
	v_mov_b32_e32 v42, v0
	v_mov_b32_e32 v43, v0
	v_mov_b32_e32 v48, v0
	v_mov_b32_e32 v49, v0
	v_mov_b32_e32 v50, v0
	v_mov_b32_e32 v51, v0
	v_mov_b32_e32 v12, v0
	v_mov_b32_e32 v13, v0
	v_mov_b32_e32 v14, v0
	v_mov_b32_e32 v15, v0
	v_mov_b32_e32 v20, v0
	v_mov_b32_e32 v21, v0
	v_mov_b32_e32 v22, v0
	v_mov_b32_e32 v23, v0
	v_mov_b32_e32 v28, v0
	v_mov_b32_e32 v29, v0
	v_mov_b32_e32 v30, v0
	v_mov_b32_e32 v31, v0
	v_mov_b32_e32 v36, v0
	v_mov_b32_e32 v37, v0
	v_mov_b32_e32 v38, v0
	v_mov_b32_e32 v39, v0
	v_mov_b32_e32 v44, v0
	v_mov_b32_e32 v45, v0
	v_mov_b32_e32 v46, v0
	v_mov_b32_e32 v47, v0
	v_mov_b32_e32 v52, v0
	v_mov_b32_e32 v53, v0
	v_mov_b32_e32 v54, v0
	v_mov_b32_e32 v55, v0
	v_mov_b32_e32 v56, v0
	v_mov_b32_e32 v57, v0
	v_mov_b32_e32 v58, v0
	v_mov_b32_e32 v59, v0
	v_mov_b32_e32 v60, v0
	v_mov_b32_e32 v61, v0
	v_mov_b32_e32 v62, v0
	v_mov_b32_e32 v63, v0
	v_mov_b32_e32 v64, v0
	v_mov_b32_e32 v65, v0
	v_mov_b32_e32 v66, v0
	v_mov_b32_e32 v67, v0
	v_mov_b32_e32 v68, v0
	v_mov_b32_e32 v69, v0
	v_mov_b32_e32 v70, v0
	v_mov_b32_e32 v71, v0
	v_mov_b32_e32 v72, v0
	v_mov_b32_e32 v73, v0
	v_mov_b32_e32 v74, v0
	v_mov_b32_e32 v75, v0
	v_mov_b32_e32 v80, v0
	v_mov_b32_e32 v81, v0
	v_mov_b32_e32 v82, v0
	v_mov_b32_e32 v83, v0
	v_mov_b32_e32 v88, v0
	v_mov_b32_e32 v89, v0
	v_mov_b32_e32 v90, v0
	v_mov_b32_e32 v91, v0
	v_mov_b32_e32 v96, v0
	v_mov_b32_e32 v97, v0
	v_mov_b32_e32 v98, v0
	v_mov_b32_e32 v99, v0
	v_mov_b32_e32 v104, v0
	v_mov_b32_e32 v105, v0
	v_mov_b32_e32 v106, v0
	v_mov_b32_e32 v107, v0
	v_mov_b32_e32 v112, v0
	v_mov_b32_e32 v113, v0
	v_mov_b32_e32 v114, v0
	v_mov_b32_e32 v115, v0
	v_mov_b32_e32 v76, v0
	v_mov_b32_e32 v77, v0
	v_mov_b32_e32 v78, v0
	v_mov_b32_e32 v79, v0
	v_mov_b32_e32 v84, v0
	v_mov_b32_e32 v85, v0
	v_mov_b32_e32 v86, v0
	v_mov_b32_e32 v87, v0
	v_mov_b32_e32 v92, v0
	v_mov_b32_e32 v93, v0
	v_mov_b32_e32 v94, v0
	v_mov_b32_e32 v95, v0
	v_mov_b32_e32 v100, v0
	v_mov_b32_e32 v101, v0
	v_mov_b32_e32 v102, v0
	v_mov_b32_e32 v103, v0
	v_mov_b32_e32 v108, v0
	v_mov_b32_e32 v109, v0
	v_mov_b32_e32 v110, v0
	v_mov_b32_e32 v111, v0
	v_mov_b32_e32 v116, v0
	v_mov_b32_e32 v117, v0
	v_mov_b32_e32 v118, v0
	v_mov_b32_e32 v119, v0
	v_mov_b32_e32 v120, v0
	v_mov_b32_e32 v121, v0
	v_mov_b32_e32 v122, v0
	v_mov_b32_e32 v123, v0
	v_mov_b32_e32 v124, v0
	v_mov_b32_e32 v125, v0
	v_mov_b32_e32 v126, v0
	v_mov_b32_e32 v127, v0
	.p2align 6

; template <class Epi, class Map>
; __device__ __forceinline__ void gemm_phase(LAS unsigned char* lds, const Gemm g, const Sched<Map>& S, const Epi& E) {
;     ...
;         const char* nA = has_next ? (const char*)g.A + nxt.aoff : cA; const char* nB = has_next ? (const char*)g.Bt + nxt.boff : cB;
; #pragma unroll 1
;         for (int t = 0; t < nt; t += 2) {
;             const bool last = (t == nt - 2);
;             const char* a1 = cA + (size_t)(t + 1) * kstep;
;             const char* a2 = last ? nA : cA + (size_t)(t + 2) * kstep; const char* b2 = last ? nB : cB + (size_t)(t + 2) * kstep;
;             const char* a3 = a2 + kstep; const char* b3 = b2 + kstep;
;     ...
; #pragma unroll
;         for (int a = 0; a < 2; ++a)
; #pragma unroll
;             for (int b = 0; b < 2; ++b)
; #pragma unroll
;                 for (int m = 0; m < 4; ++m)
; #pragma unroll
;                     for (int n = 0; n < 2; ++n) acc[a][b][m][n] = (f32x4){0.f, 0.f, 0.f, 0.f};
;         cur = nxt; cA = nA; cB = nB; ++ui;
.LBB0_658:
	v_readlane_b32 s20, v245, 30
	v_readlane_b32 s21, v245, 31
	s_add_u32 s20, s20, s13
	s_addc_u32 s21, s21, 0
	s_and_b64 s[24:25], s[42:43], exec
	v_readlane_b32 s24, v246, 17
	s_cselect_b32 s15, s21, s31
	s_cselect_b32 s33, s20, s30
	v_readlane_b32 s25, v246, 18
	s_add_u32 s24, s24, s12
	s_addc_u32 s25, s25, 0
	s_and_b64 s[34:35], s[42:43], exec
	v_mov_b32_e32 v0, 0
	s_cselect_b32 s38, s25, s29
	s_cselect_b32 s39, s24, s28
	s_mov_b64 s[44:45], 0
	s_mov_b64 s[34:35], -1
	s_mov_b64 s[36:37], 0
	v_mov_b32_e32 v1, v0
	v_mov_b32_e32 v2, v0
	v_mov_b32_e32 v3, v0
	v_mov_b32_e32 v4, v0
	v_mov_b32_e32 v5, v0
	v_mov_b32_e32 v6, v0
	v_mov_b32_e32 v7, v0
	v_mov_b32_e32 v8, v0
	v_mov_b32_e32 v9, v0
	v_mov_b32_e32 v10, v0
	v_mov_b32_e32 v11, v0
	v_mov_b32_e32 v12, v0
	v_mov_b32_e32 v13, v0
	v_mov_b32_e32 v14, v0
	v_mov_b32_e32 v15, v0
	v_mov_b32_e32 v16, v0
	v_mov_b32_e32 v17, v0
	v_mov_b32_e32 v18, v0
	v_mov_b32_e32 v19, v0
	v_mov_b32_e32 v20, v0
	v_mov_b32_e32 v21, v0
	v_mov_b32_e32 v22, v0
	v_mov_b32_e32 v23, v0
	v_mov_b32_e32 v24, v0
	v_mov_b32_e32 v25, v0
	v_mov_b32_e32 v26, v0
	v_mov_b32_e32 v27, v0
	v_mov_b32_e32 v28, v0
	v_mov_b32_e32 v29, v0
	v_mov_b32_e32 v30, v0
	v_mov_b32_e32 v31, v0
	v_mov_b32_e32 v64, v0
	v_mov_b32_e32 v65, v0
	v_mov_b32_e32 v66, v0
	v_mov_b32_e32 v67, v0
	v_mov_b32_e32 v68, v0
	v_mov_b32_e32 v69, v0
	v_mov_b32_e32 v70, v0
	v_mov_b32_e32 v71, v0
	v_mov_b32_e32 v72, v0
	v_mov_b32_e32 v73, v0
	v_mov_b32_e32 v74, v0
	v_mov_b32_e32 v75, v0
	v_mov_b32_e32 v76, v0
	v_mov_b32_e32 v77, v0
	v_mov_b32_e32 v78, v0
	v_mov_b32_e32 v79, v0
	v_mov_b32_e32 v80, v0
	v_mov_b32_e32 v81, v0
	v_mov_b32_e32 v82, v0
	v_mov_b32_e32 v83, v0
	v_mov_b32_e32 v84, v0
	v_mov_b32_e32 v85, v0
	v_mov_b32_e32 v86, v0
	v_mov_b32_e32 v87, v0
	v_mov_b32_e32 v88, v0
	v_mov_b32_e32 v89, v0
	v_mov_b32_e32 v90, v0
	v_mov_b32_e32 v91, v0
	v_mov_b32_e32 v92, v0
	v_mov_b32_e32 v93, v0
	v_mov_b32_e32 v94, v0
	v_mov_b32_e32 v95, v0
	v_mov_b32_e32 v32, v0
	v_mov_b32_e32 v33, v0
	v_mov_b32_e32 v34, v0
	v_mov_b32_e32 v35, v0
	v_mov_b32_e32 v36, v0
	v_mov_b32_e32 v37, v0
	v_mov_b32_e32 v38, v0
	v_mov_b32_e32 v39, v0
	v_mov_b32_e32 v40, v0
	v_mov_b32_e32 v41, v0
	v_mov_b32_e32 v42, v0
	v_mov_b32_e32 v43, v0
	v_mov_b32_e32 v44, v0
	v_mov_b32_e32 v45, v0
	v_mov_b32_e32 v46, v0
	v_mov_b32_e32 v47, v0
	v_mov_b32_e32 v48, v0
	v_mov_b32_e32 v49, v0
	v_mov_b32_e32 v50, v0
	v_mov_b32_e32 v51, v0
	v_mov_b32_e32 v52, v0
	v_mov_b32_e32 v53, v0
	v_mov_b32_e32 v54, v0
	v_mov_b32_e32 v55, v0
	v_mov_b32_e32 v56, v0
	v_mov_b32_e32 v57, v0
	v_mov_b32_e32 v58, v0
	v_mov_b32_e32 v59, v0
	v_mov_b32_e32 v60, v0
	v_mov_b32_e32 v61, v0
	v_mov_b32_e32 v62, v0
	v_mov_b32_e32 v63, v0
	v_mov_b32_e32 v96, v0
	v_mov_b32_e32 v97, v0
	v_mov_b32_e32 v98, v0
	v_mov_b32_e32 v99, v0
	v_mov_b32_e32 v100, v0
	v_mov_b32_e32 v101, v0
	v_mov_b32_e32 v102, v0
	v_mov_b32_e32 v103, v0
	v_mov_b32_e32 v104, v0
	v_mov_b32_e32 v105, v0
	v_mov_b32_e32 v106, v0
	v_mov_b32_e32 v107, v0
	v_mov_b32_e32 v108, v0
	v_mov_b32_e32 v109, v0
	v_mov_b32_e32 v110, v0
	v_mov_b32_e32 v111, v0
	v_mov_b32_e32 v112, v0
	v_mov_b32_e32 v113, v0
	v_mov_b32_e32 v114, v0
	v_mov_b32_e32 v115, v0
	v_mov_b32_e32 v116, v0
	v_mov_b32_e32 v117, v0
	v_mov_b32_e32 v118, v0
	v_mov_b32_e32 v119, v0
	v_mov_b32_e32 v120, v0
	v_mov_b32_e32 v121, v0
	v_mov_b32_e32 v122, v0
	v_mov_b32_e32 v123, v0
	v_mov_b32_e32 v124, v0
	v_mov_b32_e32 v125, v0
	v_mov_b32_e32 v126, v0
	v_mov_b32_e32 v127, v0
	.p2align 6

; template <class Epi, class Map>
; __device__ __forceinline__ void gemm_phase(LAS unsigned char* lds, const Gemm g, const Sched<Map>& S, const Epi& E) {
;     ...
;         const char* nA = has_next ? (const char*)g.A + nxt.aoff : cA; const char* nB = has_next ? (const char*)g.Bt + nxt.boff : cB;
; #pragma unroll 1
;         for (int t = 0; t < nt; t += 2) {
;             const bool last = (t == nt - 2);
;             const char* a1 = cA + (size_t)(t + 1) * kstep;
;             const char* a2 = last ? nA : cA + (size_t)(t + 2) * kstep; const char* b2 = last ? nB : cB + (size_t)(t + 2) * kstep;
;             const char* a3 = a2 + kstep; const char* b3 = b2 + kstep;
;     ...
; #pragma unroll
;         for (int a = 0; a < 2; ++a)
; #pragma unroll
;             for (int b = 0; b < 2; ++b)
; #pragma unroll
;                 for (int m = 0; m < 4; ++m)
; #pragma unroll
;                     for (int n = 0; n < 2; ++n) acc[a][b][m][n] = (f32x4){0.f, 0.f, 0.f, 0.f};
;         cur = nxt; cA = nA; cB = nB; ++ui;
.LBB0_678:
	v_readlane_b32 s12, v246, 43
	s_add_u32 s24, s12, s11
	v_readlane_b32 s12, v246, 44
	s_addc_u32 s25, s12, 0
	s_and_b64 s[12:13], s[42:43], exec
	s_cselect_b32 s12, s25, s35
	s_cselect_b32 s13, s24, s34
	s_add_u32 s28, s76, s10
	s_addc_u32 s29, s64, 0
	s_and_b64 s[14:15], s[42:43], exec
	v_mov_b32_e32 v0, 0
	s_cselect_b32 s14, s29, s31
	s_cselect_b32 s15, s28, s30
	s_mov_b64 s[46:47], 0
	s_mov_b64 s[36:37], -1
	s_mov_b64 s[44:45], 0
	v_mov_b32_e32 v1, v0
	v_mov_b32_e32 v2, v0
	v_mov_b32_e32 v3, v0
	v_mov_b32_e32 v4, v0
	v_mov_b32_e32 v5, v0
	v_mov_b32_e32 v6, v0
	v_mov_b32_e32 v7, v0
	v_mov_b32_e32 v8, v0
	v_mov_b32_e32 v9, v0
	v_mov_b32_e32 v10, v0
	v_mov_b32_e32 v11, v0
	v_mov_b32_e32 v16, v0
	v_mov_b32_e32 v17, v0
	v_mov_b32_e32 v18, v0
	v_mov_b32_e32 v19, v0
	v_mov_b32_e32 v24, v0
	v_mov_b32_e32 v25, v0
	v_mov_b32_e32 v26, v0
	v_mov_b32_e32 v27, v0
	v_mov_b32_e32 v32, v0
	v_mov_b32_e32 v33, v0
	v_mov_b32_e32 v34, v0
	v_mov_b32_e32 v35, v0
	v_mov_b32_e32 v40, v0
	v_mov_b32_e32 v41, v0
	v_mov_b32_e32 v42, v0
	v_mov_b32_e32 v43, v0
	v_mov_b32_e32 v48, v0
	v_mov_b32_e32 v49, v0
	v_mov_b32_e32 v50, v0
	v_mov_b32_e32 v51, v0
	v_mov_b32_e32 v12, v0
	v_mov_b32_e32 v13, v0
	v_mov_b32_e32 v14, v0
	v_mov_b32_e32 v15, v0
	v_mov_b32_e32 v20, v0
	v_mov_b32_e32 v21, v0
	v_mov_b32_e32 v22, v0
	v_mov_b32_e32 v23, v0
	v_mov_b32_e32 v28, v0
	v_mov_b32_e32 v29, v0
	v_mov_b32_e32 v30, v0
	v_mov_b32_e32 v31, v0
	v_mov_b32_e32 v36, v0
	v_mov_b32_e32 v37, v0
	v_mov_b32_e32 v38, v0
	v_mov_b32_e32 v39, v0
	v_mov_b32_e32 v44, v0
	v_mov_b32_e32 v45, v0
	v_mov_b32_e32 v46, v0
	v_mov_b32_e32 v47, v0
	v_mov_b32_e32 v52, v0
	v_mov_b32_e32 v53, v0
	v_mov_b32_e32 v54, v0
	v_mov_b32_e32 v55, v0
	v_mov_b32_e32 v56, v0
	v_mov_b32_e32 v57, v0
	v_mov_b32_e32 v58, v0
	v_mov_b32_e32 v59, v0
	v_mov_b32_e32 v60, v0
	v_mov_b32_e32 v61, v0
	v_mov_b32_e32 v62, v0
	v_mov_b32_e32 v63, v0
	v_mov_b32_e32 v64, v0
	v_mov_b32_e32 v65, v0
	v_mov_b32_e32 v66, v0
	v_mov_b32_e32 v67, v0
	v_mov_b32_e32 v68, v0
	v_mov_b32_e32 v69, v0
	v_mov_b32_e32 v70, v0
	v_mov_b32_e32 v71, v0
	v_mov_b32_e32 v72, v0
	v_mov_b32_e32 v73, v0
	v_mov_b32_e32 v74, v0
	v_mov_b32_e32 v75, v0
	v_mov_b32_e32 v80, v0
	v_mov_b32_e32 v81, v0
	v_mov_b32_e32 v82, v0
	v_mov_b32_e32 v83, v0
	v_mov_b32_e32 v88, v0
	v_mov_b32_e32 v89, v0
	v_mov_b32_e32 v90, v0
	v_mov_b32_e32 v91, v0
	v_mov_b32_e32 v96, v0
	v_mov_b32_e32 v97, v0
	v_mov_b32_e32 v98, v0
	v_mov_b32_e32 v99, v0
	v_mov_b32_e32 v104, v0
	v_mov_b32_e32 v105, v0
	v_mov_b32_e32 v106, v0
	v_mov_b32_e32 v107, v0
	v_mov_b32_e32 v112, v0
	v_mov_b32_e32 v113, v0
	v_mov_b32_e32 v114, v0
	v_mov_b32_e32 v115, v0
	v_mov_b32_e32 v76, v0
	v_mov_b32_e32 v77, v0
	v_mov_b32_e32 v78, v0
	v_mov_b32_e32 v79, v0
	v_mov_b32_e32 v84, v0
	v_mov_b32_e32 v85, v0
	v_mov_b32_e32 v86, v0
	v_mov_b32_e32 v87, v0
	v_mov_b32_e32 v92, v0
	v_mov_b32_e32 v93, v0
	v_mov_b32_e32 v94, v0
	v_mov_b32_e32 v95, v0
	v_mov_b32_e32 v100, v0
	v_mov_b32_e32 v101, v0
	v_mov_b32_e32 v102, v0
	v_mov_b32_e32 v103, v0
	v_mov_b32_e32 v108, v0
	v_mov_b32_e32 v109, v0
	v_mov_b32_e32 v110, v0
	v_mov_b32_e32 v111, v0
	v_mov_b32_e32 v116, v0
	v_mov_b32_e32 v117, v0
	v_mov_b32_e32 v118, v0
	v_mov_b32_e32 v119, v0
	v_mov_b32_e32 v120, v0
	v_mov_b32_e32 v121, v0
	v_mov_b32_e32 v122, v0
	v_mov_b32_e32 v123, v0
	v_mov_b32_e32 v124, v0
	v_mov_b32_e32 v125, v0
	v_mov_b32_e32 v126, v0
	v_mov_b32_e32 v127, v0
	.p2align 6

; template <class Epi, class Map>
; __device__ __forceinline__ void gemm_phase(LAS unsigned char* lds, const Gemm g, const Sched<Map>& S, const Epi& E) {
;     ...
;         const char* nA = has_next ? (const char*)g.A + nxt.aoff : cA; const char* nB = has_next ? (const char*)g.Bt + nxt.boff : cB;
; #pragma unroll 1
;         for (int t = 0; t < nt; t += 2) {
;             const bool last = (t == nt - 2);
;             const char* a1 = cA + (size_t)(t + 1) * kstep;
;             const char* a2 = last ? nA : cA + (size_t)(t + 2) * kstep; const char* b2 = last ? nB : cB + (size_t)(t + 2) * kstep;
;             const char* a3 = a2 + kstep; const char* b3 = b2 + kstep;
;     ...
; #pragma unroll
;         for (int a = 0; a < 2; ++a)
; #pragma unroll
;             for (int b = 0; b < 2; ++b)
; #pragma unroll
;                 for (int m = 0; m < 4; ++m)
; #pragma unroll
;                     for (int n = 0; n < 2; ++n) acc[a][b][m][n] = (f32x4){0.f, 0.f, 0.f, 0.f};
;         cur = nxt; cA = nA; cB = nB; ++ui;
.LBB0_807:
	v_readlane_b32 s28, v245, 30
	v_readlane_b32 s29, v245, 31
	s_add_u32 s28, s28, s11
	s_addc_u32 s29, s29, 0
	s_and_b64 s[30:31], s[42:43], exec
	v_readlane_b32 s30, v246, 43
	s_cselect_b32 s21, s29, s35
	s_cselect_b32 s25, s28, s34
	s_add_u32 s30, s30, s12
	v_readlane_b32 s31, v246, 44
	s_addc_u32 s31, s31, 0
	s_and_b64 s[38:39], s[42:43], exec
	s_cselect_b32 s33, s31, s37
	s_cselect_b32 s38, s30, s36
	s_add_u32 s34, s34, 0x20080
	s_addc_u32 s35, s35, 0
	s_add_u32 s39, s36, 0x100
	v_mov_b32_e32 v0, 0
	s_addc_u32 s46, s37, 0
	s_mov_b32 s47, -2
	v_mov_b32_e32 v1, v0
	v_mov_b32_e32 v2, v0
	v_mov_b32_e32 v3, v0
	v_mov_b32_e32 v4, v0
	v_mov_b32_e32 v5, v0
	v_mov_b32_e32 v6, v0
	v_mov_b32_e32 v7, v0
	v_mov_b32_e32 v8, v0
	v_mov_b32_e32 v9, v0
	v_mov_b32_e32 v10, v0
	v_mov_b32_e32 v11, v0
	v_mov_b32_e32 v12, v0
	v_mov_b32_e32 v13, v0
	v_mov_b32_e32 v14, v0
	v_mov_b32_e32 v15, v0
	v_mov_b32_e32 v16, v0
	v_mov_b32_e32 v17, v0
	v_mov_b32_e32 v18, v0
	v_mov_b32_e32 v19, v0
	v_mov_b32_e32 v20, v0
	v_mov_b32_e32 v21, v0
	v_mov_b32_e32 v22, v0
	v_mov_b32_e32 v23, v0
	v_mov_b32_e32 v24, v0
	v_mov_b32_e32 v25, v0
	v_mov_b32_e32 v26, v0
	v_mov_b32_e32 v27, v0
	v_mov_b32_e32 v28, v0
	v_mov_b32_e32 v29, v0
	v_mov_b32_e32 v30, v0
	v_mov_b32_e32 v31, v0
	v_mov_b32_e32 v32, v0
	v_mov_b32_e32 v33, v0
	v_mov_b32_e32 v34, v0
	v_mov_b32_e32 v35, v0
	v_mov_b32_e32 v36, v0
	v_mov_b32_e32 v37, v0
	v_mov_b32_e32 v38, v0
	v_mov_b32_e32 v39, v0
	v_mov_b32_e32 v40, v0
	v_mov_b32_e32 v41, v0
	v_mov_b32_e32 v42, v0
	v_mov_b32_e32 v43, v0
	v_mov_b32_e32 v44, v0
	v_mov_b32_e32 v45, v0
	v_mov_b32_e32 v46, v0
	v_mov_b32_e32 v47, v0
	v_mov_b32_e32 v48, v0
	v_mov_b32_e32 v49, v0
	v_mov_b32_e32 v50, v0
	v_mov_b32_e32 v51, v0
	v_mov_b32_e32 v52, v0
	v_mov_b32_e32 v53, v0
	v_mov_b32_e32 v54, v0
	v_mov_b32_e32 v55, v0
	v_mov_b32_e32 v56, v0
	v_mov_b32_e32 v57, v0
	v_mov_b32_e32 v58, v0
	v_mov_b32_e32 v59, v0
	v_mov_b32_e32 v60, v0
	v_mov_b32_e32 v61, v0
	v_mov_b32_e32 v62, v0
	v_mov_b32_e32 v63, v0
	v_mov_b32_e32 v64, v0
	v_mov_b32_e32 v65, v0
	v_mov_b32_e32 v66, v0
	v_mov_b32_e32 v67, v0
	v_mov_b32_e32 v68, v0
	v_mov_b32_e32 v69, v0
	v_mov_b32_e32 v70, v0
	v_mov_b32_e32 v71, v0
	v_mov_b32_e32 v72, v0
	v_mov_b32_e32 v73, v0
	v_mov_b32_e32 v74, v0
	v_mov_b32_e32 v75, v0
	v_mov_b32_e32 v76, v0
	v_mov_b32_e32 v77, v0
	v_mov_b32_e32 v78, v0
	v_mov_b32_e32 v79, v0
	v_mov_b32_e32 v80, v0
	v_mov_b32_e32 v81, v0
	v_mov_b32_e32 v82, v0
	v_mov_b32_e32 v83, v0
	v_mov_b32_e32 v84, v0
	v_mov_b32_e32 v85, v0
	v_mov_b32_e32 v86, v0
	v_mov_b32_e32 v87, v0
	v_mov_b32_e32 v88, v0
	v_mov_b32_e32 v89, v0
	v_mov_b32_e32 v90, v0
	v_mov_b32_e32 v91, v0
	v_mov_b32_e32 v92, v0
	v_mov_b32_e32 v93, v0
	v_mov_b32_e32 v94, v0
	v_mov_b32_e32 v95, v0
	v_mov_b32_e32 v96, v0
	v_mov_b32_e32 v97, v0
	v_mov_b32_e32 v98, v0
	v_mov_b32_e32 v99, v0
	v_mov_b32_e32 v100, v0
	v_mov_b32_e32 v101, v0
	v_mov_b32_e32 v102, v0
	v_mov_b32_e32 v103, v0
	v_mov_b32_e32 v104, v0
	v_mov_b32_e32 v105, v0
	v_mov_b32_e32 v106, v0
	v_mov_b32_e32 v107, v0
	v_mov_b32_e32 v108, v0
	v_mov_b32_e32 v109, v0
	v_mov_b32_e32 v110, v0
	v_mov_b32_e32 v111, v0
	v_mov_b32_e32 v112, v0
	v_mov_b32_e32 v113, v0
	v_mov_b32_e32 v114, v0
	v_mov_b32_e32 v115, v0
	v_mov_b32_e32 v116, v0
	v_mov_b32_e32 v117, v0
	v_mov_b32_e32 v118, v0
	v_mov_b32_e32 v119, v0
	v_mov_b32_e32 v120, v0
	v_mov_b32_e32 v121, v0
	v_mov_b32_e32 v122, v0
	v_mov_b32_e32 v123, v0
	v_mov_b32_e32 v124, v0
	v_mov_b32_e32 v125, v0
	v_mov_b32_e32 v126, v0
	v_mov_b32_e32 v127, v0
	.p2align 6

; #define PG8_WAIT_V(n) asm volatile("s_waitcnt vmcnt(" #n ")" ::: "memory")
; #define PG8_WAIT_L(n) asm volatile("s_waitcnt lgkmcnt(" #n ")" ::: "memory")
; template <class Epi, class Map>
; __device__ __forceinline__ void gemm_phase(LAS unsigned char* lds, const Gemm g, const Sched<Map>& S, const Epi& E) {
;     ...
;         const bool has_next = S.next(ui + 1, nxt);
;         const char* nA = has_next ? (const char*)g.A + nxt.aoff : cA; const char* nB = has_next ? (const char*)g.Bt + nxt.boff : cB;
; #pragma unroll 1
;         for (int t = 0; t < nt; t += 2) {
;             const bool last = (t == nt - 2);
;             const char* a1 = cA + (size_t)(t + 1) * kstep;
;             const char* a2 = last ? nA : cA + (size_t)(t + 2) * kstep; const char* b2 = last ? nB : cB + (size_t)(t + 2) * kstep;
;             const char* a3 = a2 + kstep; const char* b3 = b2 + kstep;
;             PG8_LDB(B0, 0, 0); PG8_LDB(B1, 0, 1); PG8_SCHED; PG8_LDA(At, 0, 0); PG8_STAGE(PG8_SA(1, 1), a1 + hstepA, voffA);
;             PG8_WAIT_V(8); PG8_WAIT_L(0); PG8_BAR; PG8_MMA(0, 0, At, B0); PG8_MMA(0, 1, At, B1); PG8_BAR; PG8_SCHED;
;             PG8_LDA(At, 0, 1); PG8_STAGE(PG8_SB(0, 0), b2, voffB); PG8_STAGE(PG8_SB(0, 1), b2 + hstepB, voffB); PG8_STAGE(PG8_SA(0, 0), a2, voffA);
;             PG8_WAIT_V(8); PG8_WAIT_L(0); PG8_BAR; PG8_MMA(1, 0, At, B0); PG8_MMA(1, 1, At, B1); PG8_BAR; PG8_SCHED;
;             PG8_LDB(B0, 1, 0); PG8_LDB(B1, 1, 1); PG8_SCHED; PG8_LDA(At, 1, 0); PG8_STAGE(PG8_SA(0, 1), a2 + hstepA, voffA);
;             PG8_WAIT_V(8); PG8_WAIT_L(0); PG8_BAR; PG8_MMA(0, 0, At, B0); PG8_MMA(0, 1, At, B1); PG8_BAR; PG8_SCHED;
;             PG8_LDA(At, 1, 1); PG8_STAGE(PG8_SB(1, 0), b3, voffB); PG8_STAGE(PG8_SB(1, 1), b3 + hstepB, voffB); PG8_STAGE(PG8_SA(1, 0), a3, voffA);
;             PG8_WAIT_V(8); PG8_WAIT_L(0); PG8_BAR; PG8_MMA(1, 0, At, B0); PG8_MMA(1, 1, At, B1); PG8_BAR; PG8_SCHED;
;         }
;         if (wr == 0) PG8_BAR;
;         E(acc, cur, wr, wc, fr, fq);
;         if (!has_next) break;
; #pragma unroll
;         for (int a = 0; a < 2; ++a)
; #pragma unroll
;             for (int b = 0; b < 2; ++b)
; #pragma unroll
;                 for (int m = 0; m < 4; ++m)
; #pragma unroll
;                     for (int n = 0; n < 2; ++n) acc[a][b][m][n] = (f32x4){0.f, 0.f, 0.f, 0.f};
;         cur = nxt; cA = nA; cB = nB; ++ui;
.LBB0_879:
	s_add_u32 s16, s78, s54
	s_addc_u32 s17, s79, 0
	s_and_b64 s[2:3], s[40:41], exec
	v_readlane_b32 s4, v246, 58
	s_cselect_b32 s2, s17, s19
	s_cselect_b32 s3, s16, s18
	s_add_u32 s46, s4, s53
	v_readlane_b32 s4, v246, 59
	s_addc_u32 s47, s4, 0
	s_and_b64 s[4:5], s[40:41], exec
	s_cselect_b32 s4, s47, s21
	s_cselect_b32 s5, s46, s20
	s_add_u32 s18, s18, 0x80080
	s_addc_u32 s19, s19, 0
	s_add_u32 s6, s20, 0x100
	v_mov_b32_e32 v0, 0
	s_addc_u32 s7, s21, 0
	s_mov_b32 s8, -2
	v_mov_b32_e32 v1, v0
	v_mov_b32_e32 v2, v0
	v_mov_b32_e32 v3, v0
	v_mov_b32_e32 v4, v0
	v_mov_b32_e32 v5, v0
	v_mov_b32_e32 v6, v0
	v_mov_b32_e32 v7, v0
	v_mov_b32_e32 v16, v0
	v_mov_b32_e32 v17, v0
	v_mov_b32_e32 v18, v0
	v_mov_b32_e32 v19, v0
	v_mov_b32_e32 v20, v0
	v_mov_b32_e32 v21, v0
	v_mov_b32_e32 v22, v0
	v_mov_b32_e32 v23, v0
	v_mov_b32_e32 v32, v0
	v_mov_b32_e32 v33, v0
	v_mov_b32_e32 v34, v0
	v_mov_b32_e32 v35, v0
	v_mov_b32_e32 v36, v0
	v_mov_b32_e32 v37, v0
	v_mov_b32_e32 v38, v0
	v_mov_b32_e32 v39, v0
	v_mov_b32_e32 v48, v0
	v_mov_b32_e32 v49, v0
	v_mov_b32_e32 v50, v0
	v_mov_b32_e32 v51, v0
	v_mov_b32_e32 v52, v0
	v_mov_b32_e32 v53, v0
	v_mov_b32_e32 v54, v0
	v_mov_b32_e32 v55, v0
	v_mov_b32_e32 v8, v0
	v_mov_b32_e32 v9, v0
	v_mov_b32_e32 v10, v0
	v_mov_b32_e32 v11, v0
	v_mov_b32_e32 v12, v0
	v_mov_b32_e32 v13, v0
	v_mov_b32_e32 v14, v0
	v_mov_b32_e32 v15, v0
	v_mov_b32_e32 v24, v0
	v_mov_b32_e32 v25, v0
	v_mov_b32_e32 v26, v0
	v_mov_b32_e32 v27, v0
	v_mov_b32_e32 v28, v0
	v_mov_b32_e32 v29, v0
	v_mov_b32_e32 v30, v0
	v_mov_b32_e32 v31, v0
	v_mov_b32_e32 v40, v0
	v_mov_b32_e32 v41, v0
	v_mov_b32_e32 v42, v0
	v_mov_b32_e32 v43, v0
	v_mov_b32_e32 v44, v0
	v_mov_b32_e32 v45, v0
	v_mov_b32_e32 v46, v0
	v_mov_b32_e32 v47, v0
	v_mov_b32_e32 v56, v0
	v_mov_b32_e32 v57, v0
	v_mov_b32_e32 v58, v0
	v_mov_b32_e32 v59, v0
	v_mov_b32_e32 v60, v0
	v_mov_b32_e32 v61, v0
	v_mov_b32_e32 v62, v0
	v_mov_b32_e32 v63, v0
	v_mov_b32_e32 v64, v0
	v_mov_b32_e32 v65, v0
	v_mov_b32_e32 v66, v0
	v_mov_b32_e32 v67, v0
	v_mov_b32_e32 v68, v0
	v_mov_b32_e32 v69, v0
	v_mov_b32_e32 v70, v0
	v_mov_b32_e32 v71, v0
	v_mov_b32_e32 v80, v0
	v_mov_b32_e32 v81, v0
	v_mov_b32_e32 v82, v0
	v_mov_b32_e32 v83, v0
	v_mov_b32_e32 v84, v0
	v_mov_b32_e32 v85, v0
	v_mov_b32_e32 v86, v0
	v_mov_b32_e32 v87, v0
	v_mov_b32_e32 v96, v0
	v_mov_b32_e32 v97, v0
	v_mov_b32_e32 v98, v0
	v_mov_b32_e32 v99, v0
	v_mov_b32_e32 v100, v0
	v_mov_b32_e32 v101, v0
	v_mov_b32_e32 v102, v0
	v_mov_b32_e32 v103, v0
	v_mov_b32_e32 v112, v0
	v_mov_b32_e32 v113, v0
	v_mov_b32_e32 v114, v0
	v_mov_b32_e32 v115, v0
	v_mov_b32_e32 v116, v0
	v_mov_b32_e32 v117, v0
	v_mov_b32_e32 v118, v0
	v_mov_b32_e32 v119, v0
	v_mov_b32_e32 v72, v0
	v_mov_b32_e32 v73, v0
	v_mov_b32_e32 v74, v0
	v_mov_b32_e32 v75, v0
	v_mov_b32_e32 v76, v0
	v_mov_b32_e32 v77, v0
	v_mov_b32_e32 v78, v0
	v_mov_b32_e32 v79, v0
	v_mov_b32_e32 v88, v0
	v_mov_b32_e32 v89, v0
	v_mov_b32_e32 v90, v0
	v_mov_b32_e32 v91, v0
	v_mov_b32_e32 v92, v0
	v_mov_b32_e32 v93, v0
	v_mov_b32_e32 v94, v0
	v_mov_b32_e32 v95, v0
	v_mov_b32_e32 v104, v0
	v_mov_b32_e32 v105, v0
	v_mov_b32_e32 v106, v0
	v_mov_b32_e32 v107, v0
	v_mov_b32_e32 v108, v0
	v_mov_b32_e32 v109, v0
	v_mov_b32_e32 v110, v0
	v_mov_b32_e32 v111, v0
	v_mov_b32_e32 v120, v0
	v_mov_b32_e32 v121, v0
	v_mov_b32_e32 v122, v0
	v_mov_b32_e32 v123, v0
	v_mov_b32_e32 v128, v0
	v_mov_b32_e32 v129, v0
	v_mov_b32_e32 v130, v0
	v_mov_b32_e32 v131, v0
	.p2align 6

; #define PG8_WAIT_V(n) asm volatile("s_waitcnt vmcnt(" #n ")" ::: "memory")
; #define PG8_WAIT_L(n) asm volatile("s_waitcnt lgkmcnt(" #n ")" ::: "memory")
; template <class Epi, class Map>
; __device__ __forceinline__ void gemm_phase(LAS unsigned char* lds, const Gemm g, const Sched<Map>& S, const Epi& E) {
;     ...
;         const bool has_next = S.next(ui + 1, nxt);
;         const char* nA = has_next ? (const char*)g.A + nxt.aoff : cA; const char* nB = has_next ? (const char*)g.Bt + nxt.boff : cB;
; #pragma unroll 1
;         for (int t = 0; t < nt; t += 2) {
;             const bool last = (t == nt - 2);
;             const char* a1 = cA + (size_t)(t + 1) * kstep;
;             const char* a2 = last ? nA : cA + (size_t)(t + 2) * kstep; const char* b2 = last ? nB : cB + (size_t)(t + 2) * kstep;
;             const char* a3 = a2 + kstep; const char* b3 = b2 + kstep;
;             PG8_LDB(B0, 0, 0); PG8_LDB(B1, 0, 1); PG8_SCHED; PG8_LDA(At, 0, 0); PG8_STAGE(PG8_SA(1, 1), a1 + hstepA, voffA);
;             PG8_WAIT_V(8); PG8_WAIT_L(0); PG8_BAR; PG8_MMA(0, 0, At, B0); PG8_MMA(0, 1, At, B1); PG8_BAR; PG8_SCHED;
;             PG8_LDA(At, 0, 1); PG8_STAGE(PG8_SB(0, 0), b2, voffB); PG8_STAGE(PG8_SB(0, 1), b2 + hstepB, voffB); PG8_STAGE(PG8_SA(0, 0), a2, voffA);
;             PG8_WAIT_V(8); PG8_WAIT_L(0); PG8_BAR; PG8_MMA(1, 0, At, B0); PG8_MMA(1, 1, At, B1); PG8_BAR; PG8_SCHED;
;             PG8_LDB(B0, 1, 0); PG8_LDB(B1, 1, 1); PG8_SCHED; PG8_LDA(At, 1, 0); PG8_STAGE(PG8_SA(0, 1), a2 + hstepA, voffA);
;             PG8_WAIT_V(8); PG8_WAIT_L(0); PG8_BAR; PG8_MMA(0, 0, At, B0); PG8_MMA(0, 1, At, B1); PG8_BAR; PG8_SCHED;
;             PG8_LDA(At, 1, 1); PG8_STAGE(PG8_SB(1, 0), b3, voffB); PG8_STAGE(PG8_SB(1, 1), b3 + hstepB, voffB); PG8_STAGE(PG8_SA(1, 0), a3, voffA);
;             PG8_WAIT_V(8); PG8_WAIT_L(0); PG8_BAR; PG8_MMA(1, 0, At, B0); PG8_MMA(1, 1, At, B1); PG8_BAR; PG8_SCHED;
;         }
;         if (wr == 0) PG8_BAR;
;         E(acc, cur, wr, wc, fr, fq);
;         if (!has_next) break;
; #pragma unroll
;         for (int a = 0; a < 2; ++a)
; #pragma unroll
;             for (int b = 0; b < 2; ++b)
; #pragma unroll
;                 for (int m = 0; m < 4; ++m)
; #pragma unroll
;                     for (int n = 0; n < 2; ++n) acc[a][b][m][n] = (f32x4){0.f, 0.f, 0.f, 0.f};
;         cur = nxt; cA = nA; cB = nB; ++ui;
.LBB0_951:
	v_readlane_b32 s30, v245, 8
	v_readlane_b32 s31, v245, 9
	s_add_u32 s30, s30, s13
	s_addc_u32 s31, s31, 0
	s_and_b64 s[34:35], s[38:39], exec
	v_readlane_b32 s34, v245, 4
	s_cselect_b32 s33, s31, s37
	s_cselect_b32 s44, s30, s36
	s_add_u32 s34, s34, s12
	v_readlane_b32 s35, v245, 5
	s_addc_u32 s35, s35, 0
	s_and_b64 s[42:43], s[38:39], exec
	s_cselect_b32 s45, s35, s41
	s_cselect_b32 s46, s34, s40
	s_add_u32 s36, s36, 0x100080
	s_addc_u32 s37, s37, 0
	s_add_u32 s47, s40, 0x100
	v_mov_b32_e32 v0, 0
	s_addc_u32 s48, s41, 0
	s_mov_b32 s49, -2
	v_mov_b32_e32 v1, v0
	v_mov_b32_e32 v2, v0
	v_mov_b32_e32 v3, v0
	v_mov_b32_e32 v4, v0
	v_mov_b32_e32 v5, v0
	v_mov_b32_e32 v6, v0
	v_mov_b32_e32 v7, v0
	v_mov_b32_e32 v12, v0
	v_mov_b32_e32 v13, v0
	v_mov_b32_e32 v14, v0
	v_mov_b32_e32 v15, v0
	v_mov_b32_e32 v16, v0
	v_mov_b32_e32 v17, v0
	v_mov_b32_e32 v18, v0
	v_mov_b32_e32 v19, v0
	v_mov_b32_e32 v32, v0
	v_mov_b32_e32 v33, v0
	v_mov_b32_e32 v34, v0
	v_mov_b32_e32 v35, v0
	v_mov_b32_e32 v36, v0
	v_mov_b32_e32 v37, v0
	v_mov_b32_e32 v38, v0
	v_mov_b32_e32 v39, v0
	v_mov_b32_e32 v40, v0
	v_mov_b32_e32 v41, v0
	v_mov_b32_e32 v42, v0
	v_mov_b32_e32 v43, v0
	v_mov_b32_e32 v44, v0
	v_mov_b32_e32 v45, v0
	v_mov_b32_e32 v46, v0
	v_mov_b32_e32 v47, v0
	v_mov_b32_e32 v8, v0
	v_mov_b32_e32 v9, v0
	v_mov_b32_e32 v10, v0
	v_mov_b32_e32 v11, v0
	v_mov_b32_e32 v20, v0
	v_mov_b32_e32 v21, v0
	v_mov_b32_e32 v22, v0
	v_mov_b32_e32 v23, v0
	v_mov_b32_e32 v24, v0
	v_mov_b32_e32 v25, v0
	v_mov_b32_e32 v26, v0
	v_mov_b32_e32 v27, v0
	v_mov_b32_e32 v28, v0
	v_mov_b32_e32 v29, v0
	v_mov_b32_e32 v30, v0
	v_mov_b32_e32 v31, v0
	v_mov_b32_e32 v48, v0
	v_mov_b32_e32 v49, v0
	v_mov_b32_e32 v50, v0
	v_mov_b32_e32 v51, v0
	v_mov_b32_e32 v52, v0
	v_mov_b32_e32 v53, v0
	v_mov_b32_e32 v54, v0
	v_mov_b32_e32 v55, v0
	v_mov_b32_e32 v56, v0
	v_mov_b32_e32 v57, v0
	v_mov_b32_e32 v58, v0
	v_mov_b32_e32 v59, v0
	v_mov_b32_e32 v60, v0
	v_mov_b32_e32 v61, v0
	v_mov_b32_e32 v62, v0
	v_mov_b32_e32 v63, v0
	v_mov_b32_e32 v76, v0
	v_mov_b32_e32 v77, v0
	v_mov_b32_e32 v78, v0
	v_mov_b32_e32 v79, v0
	v_mov_b32_e32 v80, v0
	v_mov_b32_e32 v81, v0
	v_mov_b32_e32 v82, v0
	v_mov_b32_e32 v83, v0
	v_mov_b32_e32 v84, v0
	v_mov_b32_e32 v85, v0
	v_mov_b32_e32 v86, v0
	v_mov_b32_e32 v87, v0
	v_mov_b32_e32 v88, v0
	v_mov_b32_e32 v89, v0
	v_mov_b32_e32 v90, v0
	v_mov_b32_e32 v91, v0
	v_mov_b32_e32 v112, v0
	v_mov_b32_e32 v113, v0
	v_mov_b32_e32 v114, v0
	v_mov_b32_e32 v115, v0
	v_mov_b32_e32 v116, v0
	v_mov_b32_e32 v117, v0
	v_mov_b32_e32 v118, v0
	v_mov_b32_e32 v119, v0
	v_mov_b32_e32 v120, v0
	v_mov_b32_e32 v121, v0
	v_mov_b32_e32 v122, v0
	v_mov_b32_e32 v123, v0
	v_mov_b32_e32 v124, v0
	v_mov_b32_e32 v125, v0
	v_mov_b32_e32 v126, v0
	v_mov_b32_e32 v127, v0
	v_mov_b32_e32 v92, v0
	v_mov_b32_e32 v93, v0
	v_mov_b32_e32 v94, v0
	v_mov_b32_e32 v95, v0
	v_mov_b32_e32 v96, v0
	v_mov_b32_e32 v97, v0
	v_mov_b32_e32 v98, v0
	v_mov_b32_e32 v99, v0
	v_mov_b32_e32 v100, v0
	v_mov_b32_e32 v101, v0
	v_mov_b32_e32 v102, v0
	v_mov_b32_e32 v103, v0
	v_mov_b32_e32 v104, v0
	v_mov_b32_e32 v105, v0
	v_mov_b32_e32 v106, v0
	v_mov_b32_e32 v107, v0
	v_mov_b32_e32 v128, v0
	v_mov_b32_e32 v129, v0
	v_mov_b32_e32 v130, v0
	v_mov_b32_e32 v131, v0
	v_mov_b32_e32 v132, v0
	v_mov_b32_e32 v133, v0
	v_mov_b32_e32 v134, v0
	v_mov_b32_e32 v135, v0
	v_mov_b32_e32 v136, v0
	v_mov_b32_e32 v137, v0
	v_mov_b32_e32 v138, v0
	v_mov_b32_e32 v139, v0
	v_mov_b32_e32 v140, v0
	v_mov_b32_e32 v141, v0
	v_mov_b32_e32 v142, v0
	v_mov_b32_e32 v143, v0
	.p2align 6

; #define PG8_WAIT_V(n) asm volatile("s_waitcnt vmcnt(" #n ")" ::: "memory")
; #define PG8_WAIT_L(n) asm volatile("s_waitcnt lgkmcnt(" #n ")" ::: "memory")
; template <class Epi, class Map>
; __device__ __forceinline__ void gemm_phase(LAS unsigned char* lds, const Gemm g, const Sched<Map>& S, const Epi& E) {
;     ...
;         const bool has_next = S.next(ui + 1, nxt);
;         const char* nA = has_next ? (const char*)g.A + nxt.aoff : cA; const char* nB = has_next ? (const char*)g.Bt + nxt.boff : cB;
; #pragma unroll 1
;         for (int t = 0; t < nt; t += 2) {
;             const bool last = (t == nt - 2);
;             const char* a1 = cA + (size_t)(t + 1) * kstep;
;             const char* a2 = last ? nA : cA + (size_t)(t + 2) * kstep; const char* b2 = last ? nB : cB + (size_t)(t + 2) * kstep;
;             const char* a3 = a2 + kstep; const char* b3 = b2 + kstep;
;             PG8_LDB(B0, 0, 0); PG8_LDB(B1, 0, 1); PG8_SCHED; PG8_LDA(At, 0, 0); PG8_STAGE(PG8_SA(1, 1), a1 + hstepA, voffA);
;             PG8_WAIT_V(8); PG8_WAIT_L(0); PG8_BAR; PG8_MMA(0, 0, At, B0); PG8_MMA(0, 1, At, B1); PG8_BAR; PG8_SCHED;
;             PG8_LDA(At, 0, 1); PG8_STAGE(PG8_SB(0, 0), b2, voffB); PG8_STAGE(PG8_SB(0, 1), b2 + hstepB, voffB); PG8_STAGE(PG8_SA(0, 0), a2, voffA);
;             PG8_WAIT_V(8); PG8_WAIT_L(0); PG8_BAR; PG8_MMA(1, 0, At, B0); PG8_MMA(1, 1, At, B1); PG8_BAR; PG8_SCHED;
;             PG8_LDB(B0, 1, 0); PG8_LDB(B1, 1, 1); PG8_SCHED; PG8_LDA(At, 1, 0); PG8_STAGE(PG8_SA(0, 1), a2 + hstepA, voffA);
;             PG8_WAIT_V(8); PG8_WAIT_L(0); PG8_BAR; PG8_MMA(0, 0, At, B0); PG8_MMA(0, 1, At, B1); PG8_BAR; PG8_SCHED;
;             PG8_LDA(At, 1, 1); PG8_STAGE(PG8_SB(1, 0), b3, voffB); PG8_STAGE(PG8_SB(1, 1), b3 + hstepB, voffB); PG8_STAGE(PG8_SA(1, 0), a3, voffA);
;             PG8_WAIT_V(8); PG8_WAIT_L(0); PG8_BAR; PG8_MMA(1, 0, At, B0); PG8_MMA(1, 1, At, B1); PG8_BAR; PG8_SCHED;
;         }
;         if (wr == 0) PG8_BAR;
;         E(acc, cur, wr, wc, fr, fq);
;         if (!has_next) break;
; #pragma unroll
;         for (int a = 0; a < 2; ++a)
; #pragma unroll
;             for (int b = 0; b < 2; ++b)
; #pragma unroll
;                 for (int m = 0; m < 4; ++m)
; #pragma unroll
;                     for (int n = 0; n < 2; ++n) acc[a][b][m][n] = (f32x4){0.f, 0.f, 0.f, 0.f};
;         cur = nxt; cA = nA; cB = nB; ++ui;
.LBB0_1087:
	v_readlane_b32 s12, v245, 21
	v_readlane_b32 s13, v245, 22
	s_add_u32 s24, s12, s10
	s_addc_u32 s25, s13, 0
	s_and_b64 s[12:13], s[38:39], exec
	v_readlane_b32 s14, v244, 20
	s_cselect_b32 s12, s25, s31
	s_cselect_b32 s13, s24, s30
	s_add_u32 s28, s14, s9
	v_readlane_b32 s14, v244, 21
	s_addc_u32 s29, s14, 0
	s_and_b64 s[14:15], s[38:39], exec
	s_cselect_b32 s14, s29, s35
	s_cselect_b32 s15, s28, s34
	s_add_u32 s30, s30, 0x80080
	s_addc_u32 s31, s31, 0
	s_add_u32 s21, s34, 0x100
	v_mov_b32_e32 v0, 0
	s_addc_u32 s33, s35, 0
	s_mov_b32 s40, -2
	v_mov_b32_e32 v1, v0
	v_mov_b32_e32 v2, v0
	v_mov_b32_e32 v3, v0
	v_mov_b32_e32 v4, v0
	v_mov_b32_e32 v5, v0
	v_mov_b32_e32 v6, v0
	v_mov_b32_e32 v7, v0
	v_mov_b32_e32 v16, v0
	v_mov_b32_e32 v17, v0
	v_mov_b32_e32 v18, v0
	v_mov_b32_e32 v19, v0
	v_mov_b32_e32 v20, v0
	v_mov_b32_e32 v21, v0
	v_mov_b32_e32 v22, v0
	v_mov_b32_e32 v23, v0
	v_mov_b32_e32 v32, v0
	v_mov_b32_e32 v33, v0
	v_mov_b32_e32 v34, v0
	v_mov_b32_e32 v35, v0
	v_mov_b32_e32 v36, v0
	v_mov_b32_e32 v37, v0
	v_mov_b32_e32 v38, v0
	v_mov_b32_e32 v39, v0
	v_mov_b32_e32 v48, v0
	v_mov_b32_e32 v49, v0
	v_mov_b32_e32 v50, v0
	v_mov_b32_e32 v51, v0
	v_mov_b32_e32 v52, v0
	v_mov_b32_e32 v53, v0
	v_mov_b32_e32 v54, v0
	v_mov_b32_e32 v55, v0
	v_mov_b32_e32 v8, v0
	v_mov_b32_e32 v9, v0
	v_mov_b32_e32 v10, v0
	v_mov_b32_e32 v11, v0
	v_mov_b32_e32 v12, v0
	v_mov_b32_e32 v13, v0
	v_mov_b32_e32 v14, v0
	v_mov_b32_e32 v15, v0
	v_mov_b32_e32 v24, v0
	v_mov_b32_e32 v25, v0
	v_mov_b32_e32 v26, v0
	v_mov_b32_e32 v27, v0
	v_mov_b32_e32 v28, v0
	v_mov_b32_e32 v29, v0
	v_mov_b32_e32 v30, v0
	v_mov_b32_e32 v31, v0
	v_mov_b32_e32 v40, v0
	v_mov_b32_e32 v41, v0
	v_mov_b32_e32 v42, v0
	v_mov_b32_e32 v43, v0
	v_mov_b32_e32 v44, v0
	v_mov_b32_e32 v45, v0
	v_mov_b32_e32 v46, v0
	v_mov_b32_e32 v47, v0
	v_mov_b32_e32 v56, v0
	v_mov_b32_e32 v57, v0
	v_mov_b32_e32 v58, v0
	v_mov_b32_e32 v59, v0
	v_mov_b32_e32 v60, v0
	v_mov_b32_e32 v61, v0
	v_mov_b32_e32 v62, v0
	v_mov_b32_e32 v63, v0
	v_mov_b32_e32 v64, v0
	v_mov_b32_e32 v65, v0
	v_mov_b32_e32 v66, v0
	v_mov_b32_e32 v67, v0
	v_mov_b32_e32 v68, v0
	v_mov_b32_e32 v69, v0
	v_mov_b32_e32 v70, v0
	v_mov_b32_e32 v71, v0
	v_mov_b32_e32 v80, v0
	v_mov_b32_e32 v81, v0
	v_mov_b32_e32 v82, v0
	v_mov_b32_e32 v83, v0
	v_mov_b32_e32 v84, v0
	v_mov_b32_e32 v85, v0
	v_mov_b32_e32 v86, v0
	v_mov_b32_e32 v87, v0
	v_mov_b32_e32 v96, v0
	v_mov_b32_e32 v97, v0
	v_mov_b32_e32 v98, v0
	v_mov_b32_e32 v99, v0
	v_mov_b32_e32 v100, v0
	v_mov_b32_e32 v101, v0
	v_mov_b32_e32 v102, v0
	v_mov_b32_e32 v103, v0
	v_mov_b32_e32 v112, v0
	v_mov_b32_e32 v113, v0
	v_mov_b32_e32 v114, v0
	v_mov_b32_e32 v115, v0
	v_mov_b32_e32 v116, v0
	v_mov_b32_e32 v117, v0
	v_mov_b32_e32 v118, v0
	v_mov_b32_e32 v119, v0
	v_mov_b32_e32 v72, v0
	v_mov_b32_e32 v73, v0
	v_mov_b32_e32 v74, v0
	v_mov_b32_e32 v75, v0
	v_mov_b32_e32 v76, v0
	v_mov_b32_e32 v77, v0
	v_mov_b32_e32 v78, v0
	v_mov_b32_e32 v79, v0
	v_mov_b32_e32 v88, v0
	v_mov_b32_e32 v89, v0
	v_mov_b32_e32 v90, v0
	v_mov_b32_e32 v91, v0
	v_mov_b32_e32 v92, v0
	v_mov_b32_e32 v93, v0
	v_mov_b32_e32 v94, v0
	v_mov_b32_e32 v95, v0
	v_mov_b32_e32 v104, v0
	v_mov_b32_e32 v105, v0
	v_mov_b32_e32 v106, v0
	v_mov_b32_e32 v107, v0
	v_mov_b32_e32 v108, v0
	v_mov_b32_e32 v109, v0
	v_mov_b32_e32 v110, v0
	v_mov_b32_e32 v111, v0
	v_mov_b32_e32 v120, v0
	v_mov_b32_e32 v121, v0
	v_mov_b32_e32 v122, v0
	v_mov_b32_e32 v123, v0
	v_mov_b32_e32 v124, v0
	v_mov_b32_e32 v125, v0
	v_mov_b32_e32 v126, v0
	v_mov_b32_e32 v127, v0
	.p2align 6

; #define PG8_WAIT_V(n) asm volatile("s_waitcnt vmcnt(" #n ")" ::: "memory")
; #define PG8_WAIT_L(n) asm volatile("s_waitcnt lgkmcnt(" #n ")" ::: "memory")
; template <class Epi, class Map>
; __device__ __forceinline__ void gemm_phase(LAS unsigned char* lds, const Gemm g, const Sched<Map>& S, const Epi& E) {
;     ...
;         const bool has_next = S.next(ui + 1, nxt);
;         const char* nA = has_next ? (const char*)g.A + nxt.aoff : cA; const char* nB = has_next ? (const char*)g.Bt + nxt.boff : cB;
; #pragma unroll 1
;         for (int t = 0; t < nt; t += 2) {
;             const bool last = (t == nt - 2);
;             const char* a1 = cA + (size_t)(t + 1) * kstep;
;             const char* a2 = last ? nA : cA + (size_t)(t + 2) * kstep; const char* b2 = last ? nB : cB + (size_t)(t + 2) * kstep;
;             const char* a3 = a2 + kstep; const char* b3 = b2 + kstep;
;             PG8_LDB(B0, 0, 0); PG8_LDB(B1, 0, 1); PG8_SCHED; PG8_LDA(At, 0, 0); PG8_STAGE(PG8_SA(1, 1), a1 + hstepA, voffA);
;             PG8_WAIT_V(8); PG8_WAIT_L(0); PG8_BAR; PG8_MMA(0, 0, At, B0); PG8_MMA(0, 1, At, B1); PG8_BAR; PG8_SCHED;
;             PG8_LDA(At, 0, 1); PG8_STAGE(PG8_SB(0, 0), b2, voffB); PG8_STAGE(PG8_SB(0, 1), b2 + hstepB, voffB); PG8_STAGE(PG8_SA(0, 0), a2, voffA);
;             PG8_WAIT_V(8); PG8_WAIT_L(0); PG8_BAR; PG8_MMA(1, 0, At, B0); PG8_MMA(1, 1, At, B1); PG8_BAR; PG8_SCHED;
;             PG8_LDB(B0, 1, 0); PG8_LDB(B1, 1, 1); PG8_SCHED; PG8_LDA(At, 1, 0); PG8_STAGE(PG8_SA(0, 1), a2 + hstepA, voffA);
;             PG8_WAIT_V(8); PG8_WAIT_L(0); PG8_BAR; PG8_MMA(0, 0, At, B0); PG8_MMA(0, 1, At, B1); PG8_BAR; PG8_SCHED;
;             PG8_LDA(At, 1, 1); PG8_STAGE(PG8_SB(1, 0), b3, voffB); PG8_STAGE(PG8_SB(1, 1), b3 + hstepB, voffB); PG8_STAGE(PG8_SA(1, 0), a3, voffA);
;             PG8_WAIT_V(8); PG8_WAIT_L(0); PG8_BAR; PG8_MMA(1, 0, At, B0); PG8_MMA(1, 1, At, B1); PG8_BAR; PG8_SCHED;
;         }
;         if (wr == 0) PG8_BAR;
;         E(acc, cur, wr, wc, fr, fq);
;         if (!has_next) break;
; #pragma unroll
;         for (int a = 0; a < 2; ++a)
; #pragma unroll
;             for (int b = 0; b < 2; ++b)
; #pragma unroll
;                 for (int m = 0; m < 4; ++m)
; #pragma unroll
;                     for (int n = 0; n < 2; ++n) acc[a][b][m][n] = (f32x4){0.f, 0.f, 0.f, 0.f};
;         cur = nxt; cA = nA; cB = nB; ++ui;
.LBB0_1160:
	v_readlane_b32 s20, v245, 30
	v_readlane_b32 s21, v245, 31
	s_add_u32 s20, s20, s15
	s_addc_u32 s21, s21, 0
	s_and_b64 s[24:25], s[40:41], exec
	v_readlane_b32 s24, v244, 22
	s_cselect_b32 s37, s21, s29
	s_cselect_b32 s44, s20, s28
	s_add_u32 s24, s24, s14
	v_readlane_b32 s25, v244, 23
	s_addc_u32 s25, s25, 0
	s_and_b64 s[34:35], s[40:41], exec
	s_cselect_b32 s45, s25, s31
	s_cselect_b32 s46, s24, s30
	s_add_u32 s28, s28, 0x200080
	s_addc_u32 s29, s29, 0
	s_add_u32 s47, s30, 0x100
	v_mov_b32_e32 v0, 0
	s_addc_u32 s48, s31, 0
	s_mov_b32 s49, -2
	v_mov_b32_e32 v1, v0
	v_mov_b32_e32 v2, v0
	v_mov_b32_e32 v3, v0
	v_mov_b32_e32 v4, v0
	v_mov_b32_e32 v5, v0
	v_mov_b32_e32 v6, v0
	v_mov_b32_e32 v7, v0
	v_mov_b32_e32 v12, v0
	v_mov_b32_e32 v13, v0
	v_mov_b32_e32 v14, v0
	v_mov_b32_e32 v15, v0
	v_mov_b32_e32 v20, v0
	v_mov_b32_e32 v21, v0
	v_mov_b32_e32 v22, v0
	v_mov_b32_e32 v23, v0
	v_mov_b32_e32 v28, v0
	v_mov_b32_e32 v29, v0
	v_mov_b32_e32 v30, v0
	v_mov_b32_e32 v31, v0
	v_mov_b32_e32 v36, v0
	v_mov_b32_e32 v37, v0
	v_mov_b32_e32 v38, v0
	v_mov_b32_e32 v39, v0
	v_mov_b32_e32 v44, v0
	v_mov_b32_e32 v45, v0
	v_mov_b32_e32 v46, v0
	v_mov_b32_e32 v47, v0
	v_mov_b32_e32 v52, v0
	v_mov_b32_e32 v53, v0
	v_mov_b32_e32 v54, v0
	v_mov_b32_e32 v55, v0
	v_mov_b32_e32 v8, v0
	v_mov_b32_e32 v9, v0
	v_mov_b32_e32 v10, v0
	v_mov_b32_e32 v11, v0
	v_mov_b32_e32 v16, v0
	v_mov_b32_e32 v17, v0
	v_mov_b32_e32 v18, v0
	v_mov_b32_e32 v19, v0
	v_mov_b32_e32 v24, v0
	v_mov_b32_e32 v25, v0
	v_mov_b32_e32 v26, v0
	v_mov_b32_e32 v27, v0
	v_mov_b32_e32 v32, v0
	v_mov_b32_e32 v33, v0
	v_mov_b32_e32 v34, v0
	v_mov_b32_e32 v35, v0
	v_mov_b32_e32 v40, v0
	v_mov_b32_e32 v41, v0
	v_mov_b32_e32 v42, v0
	v_mov_b32_e32 v43, v0
	v_mov_b32_e32 v48, v0
	v_mov_b32_e32 v49, v0
	v_mov_b32_e32 v50, v0
	v_mov_b32_e32 v51, v0
	v_mov_b32_e32 v56, v0
	v_mov_b32_e32 v57, v0
	v_mov_b32_e32 v58, v0
	v_mov_b32_e32 v59, v0
	v_mov_b32_e32 v60, v0
	v_mov_b32_e32 v61, v0
	v_mov_b32_e32 v62, v0
	v_mov_b32_e32 v63, v0
	v_mov_b32_e32 v64, v0
	v_mov_b32_e32 v65, v0
	v_mov_b32_e32 v66, v0
	v_mov_b32_e32 v67, v0
	v_mov_b32_e32 v68, v0
	v_mov_b32_e32 v69, v0
	v_mov_b32_e32 v70, v0
	v_mov_b32_e32 v71, v0
	v_mov_b32_e32 v80, v0
	v_mov_b32_e32 v81, v0
	v_mov_b32_e32 v82, v0
	v_mov_b32_e32 v83, v0
	v_mov_b32_e32 v84, v0
	v_mov_b32_e32 v85, v0
	v_mov_b32_e32 v86, v0
	v_mov_b32_e32 v87, v0
	v_mov_b32_e32 v88, v0
	v_mov_b32_e32 v89, v0
	v_mov_b32_e32 v90, v0
	v_mov_b32_e32 v91, v0
	v_mov_b32_e32 v92, v0
	v_mov_b32_e32 v93, v0
	v_mov_b32_e32 v94, v0
	v_mov_b32_e32 v95, v0
	v_mov_b32_e32 v120, v0
	v_mov_b32_e32 v121, v0
	v_mov_b32_e32 v122, v0
	v_mov_b32_e32 v123, v0
	v_mov_b32_e32 v124, v0
	v_mov_b32_e32 v125, v0
	v_mov_b32_e32 v126, v0
	v_mov_b32_e32 v127, v0
	v_mov_b32_e32 v72, v0
	v_mov_b32_e32 v73, v0
	v_mov_b32_e32 v74, v0
	v_mov_b32_e32 v75, v0
	v_mov_b32_e32 v76, v0
	v_mov_b32_e32 v77, v0
	v_mov_b32_e32 v78, v0
	v_mov_b32_e32 v79, v0
	v_mov_b32_e32 v96, v0
	v_mov_b32_e32 v97, v0
	v_mov_b32_e32 v98, v0
	v_mov_b32_e32 v99, v0
	v_mov_b32_e32 v100, v0
	v_mov_b32_e32 v101, v0
	v_mov_b32_e32 v102, v0
	v_mov_b32_e32 v103, v0
	v_mov_b32_e32 v128, v0
	v_mov_b32_e32 v129, v0
	v_mov_b32_e32 v130, v0
	v_mov_b32_e32 v131, v0
	v_mov_b32_e32 v132, v0
	v_mov_b32_e32 v133, v0
	v_mov_b32_e32 v134, v0
	v_mov_b32_e32 v135, v0
	v_mov_b32_e32 v136, v0
	v_mov_b32_e32 v137, v0
	v_mov_b32_e32 v138, v0
	v_mov_b32_e32 v139, v0
	v_mov_b32_e32 v140, v0
	v_mov_b32_e32 v141, v0
	v_mov_b32_e32 v142, v0
	v_mov_b32_e32 v143, v0
	.p2align 6

; #define PG8_WAIT_V(n) asm volatile("s_waitcnt vmcnt(" #n ")" ::: "memory")
; #define PG8_WAIT_L(n) asm volatile("s_waitcnt lgkmcnt(" #n ")" ::: "memory")
; template <class Epi, class Map>
; __device__ __forceinline__ void gemm_phase(LAS unsigned char* lds, const Gemm g, const Sched<Map>& S, const Epi& E) {
;     ...
;         const bool has_next = S.next(ui + 1, nxt);
;         const char* nA = has_next ? (const char*)g.A + nxt.aoff : cA; const char* nB = has_next ? (const char*)g.Bt + nxt.boff : cB;
; #pragma unroll 1
;         for (int t = 0; t < nt; t += 2) {
;             const bool last = (t == nt - 2);
;             const char* a1 = cA + (size_t)(t + 1) * kstep;
;             const char* a2 = last ? nA : cA + (size_t)(t + 2) * kstep; const char* b2 = last ? nB : cB + (size_t)(t + 2) * kstep;
;             const char* a3 = a2 + kstep; const char* b3 = b2 + kstep;
;             PG8_LDB(B0, 0, 0); PG8_LDB(B1, 0, 1); PG8_SCHED; PG8_LDA(At, 0, 0); PG8_STAGE(PG8_SA(1, 1), a1 + hstepA, voffA);
;             PG8_WAIT_V(8); PG8_WAIT_L(0); PG8_BAR; PG8_MMA(0, 0, At, B0); PG8_MMA(0, 1, At, B1); PG8_BAR; PG8_SCHED;
;             PG8_LDA(At, 0, 1); PG8_STAGE(PG8_SB(0, 0), b2, voffB); PG8_STAGE(PG8_SB(0, 1), b2 + hstepB, voffB); PG8_STAGE(PG8_SA(0, 0), a2, voffA);
;             PG8_WAIT_V(8); PG8_WAIT_L(0); PG8_BAR; PG8_MMA(1, 0, At, B0); PG8_MMA(1, 1, At, B1); PG8_BAR; PG8_SCHED;
;             PG8_LDB(B0, 1, 0); PG8_LDB(B1, 1, 1); PG8_SCHED; PG8_LDA(At, 1, 0); PG8_STAGE(PG8_SA(0, 1), a2 + hstepA, voffA);
;             PG8_WAIT_V(8); PG8_WAIT_L(0); PG8_BAR; PG8_MMA(0, 0, At, B0); PG8_MMA(0, 1, At, B1); PG8_BAR; PG8_SCHED;
;             PG8_LDA(At, 1, 1); PG8_STAGE(PG8_SB(1, 0), b3, voffB); PG8_STAGE(PG8_SB(1, 1), b3 + hstepB, voffB); PG8_STAGE(PG8_SA(1, 0), a3, voffA);
;             PG8_WAIT_V(8); PG8_WAIT_L(0); PG8_BAR; PG8_MMA(1, 0, At, B0); PG8_MMA(1, 1, At, B1); PG8_BAR; PG8_SCHED;
;         }
;         if (wr == 0) PG8_BAR;
;         E(acc, cur, wr, wc, fr, fq);
;         if (!has_next) break;
; #pragma unroll
;         for (int a = 0; a < 2; ++a)
; #pragma unroll
;             for (int b = 0; b < 2; ++b)
; #pragma unroll
;                 for (int m = 0; m < 4; ++m)
; #pragma unroll
;                     for (int n = 0; n < 2; ++n) acc[a][b][m][n] = (f32x4){0.f, 0.f, 0.f, 0.f};
;         cur = nxt; cA = nA; cB = nB; ++ui;
.LBB0_1182:
	v_readlane_b32 s20, v245, 30
	v_readlane_b32 s21, v245, 31
	s_add_u32 s20, s20, s15
	s_addc_u32 s21, s21, 0
	s_and_b64 s[24:25], s[38:39], exec
	v_readlane_b32 s24, v244, 22
	s_cselect_b32 s37, s21, s29
	s_cselect_b32 s40, s20, s28
	s_add_u32 s24, s24, s14
	v_readlane_b32 s25, v244, 23
	s_addc_u32 s25, s25, 0
	s_and_b64 s[34:35], s[38:39], exec
	s_cselect_b32 s41, s25, s31
	s_cselect_b32 s44, s24, s30
	s_add_u32 s28, s28, 0x200080
	s_addc_u32 s29, s29, 0
	s_add_u32 s45, s30, 0x100
	v_mov_b32_e32 v0, 0
	s_addc_u32 s46, s31, 0
	s_mov_b32 s47, -2
	v_mov_b32_e32 v1, v0
	v_mov_b32_e32 v2, v0
	v_mov_b32_e32 v3, v0
	v_mov_b32_e32 v4, v0
	v_mov_b32_e32 v5, v0
	v_mov_b32_e32 v6, v0
	v_mov_b32_e32 v7, v0
	v_mov_b32_e32 v12, v0
	v_mov_b32_e32 v13, v0
	v_mov_b32_e32 v14, v0
	v_mov_b32_e32 v15, v0
	v_mov_b32_e32 v16, v0
	v_mov_b32_e32 v17, v0
	v_mov_b32_e32 v18, v0
	v_mov_b32_e32 v19, v0
	v_mov_b32_e32 v32, v0
	v_mov_b32_e32 v33, v0
	v_mov_b32_e32 v34, v0
	v_mov_b32_e32 v35, v0
	v_mov_b32_e32 v36, v0
	v_mov_b32_e32 v37, v0
	v_mov_b32_e32 v38, v0
	v_mov_b32_e32 v39, v0
	v_mov_b32_e32 v40, v0
	v_mov_b32_e32 v41, v0
	v_mov_b32_e32 v42, v0
	v_mov_b32_e32 v43, v0
	v_mov_b32_e32 v44, v0
	v_mov_b32_e32 v45, v0
	v_mov_b32_e32 v46, v0
	v_mov_b32_e32 v47, v0
	v_mov_b32_e32 v8, v0
	v_mov_b32_e32 v9, v0
	v_mov_b32_e32 v10, v0
	v_mov_b32_e32 v11, v0
	v_mov_b32_e32 v20, v0
	v_mov_b32_e32 v21, v0
	v_mov_b32_e32 v22, v0
	v_mov_b32_e32 v23, v0
	v_mov_b32_e32 v24, v0
	v_mov_b32_e32 v25, v0
	v_mov_b32_e32 v26, v0
	v_mov_b32_e32 v27, v0
	v_mov_b32_e32 v28, v0
	v_mov_b32_e32 v29, v0
	v_mov_b32_e32 v30, v0
	v_mov_b32_e32 v31, v0
	v_mov_b32_e32 v48, v0
	v_mov_b32_e32 v49, v0
	v_mov_b32_e32 v50, v0
	v_mov_b32_e32 v51, v0
	v_mov_b32_e32 v52, v0
	v_mov_b32_e32 v53, v0
	v_mov_b32_e32 v54, v0
	v_mov_b32_e32 v55, v0
	v_mov_b32_e32 v56, v0
	v_mov_b32_e32 v57, v0
	v_mov_b32_e32 v58, v0
	v_mov_b32_e32 v59, v0
	v_mov_b32_e32 v60, v0
	v_mov_b32_e32 v61, v0
	v_mov_b32_e32 v62, v0
	v_mov_b32_e32 v63, v0
	v_mov_b32_e32 v76, v0
	v_mov_b32_e32 v77, v0
	v_mov_b32_e32 v78, v0
	v_mov_b32_e32 v79, v0
	v_mov_b32_e32 v80, v0
	v_mov_b32_e32 v81, v0
	v_mov_b32_e32 v82, v0
	v_mov_b32_e32 v83, v0
	v_mov_b32_e32 v84, v0
	v_mov_b32_e32 v85, v0
	v_mov_b32_e32 v86, v0
	v_mov_b32_e32 v87, v0
	v_mov_b32_e32 v88, v0
	v_mov_b32_e32 v89, v0
	v_mov_b32_e32 v90, v0
	v_mov_b32_e32 v91, v0
	v_mov_b32_e32 v112, v0
	v_mov_b32_e32 v113, v0
	v_mov_b32_e32 v114, v0
	v_mov_b32_e32 v115, v0
	v_mov_b32_e32 v116, v0
	v_mov_b32_e32 v117, v0
	v_mov_b32_e32 v118, v0
	v_mov_b32_e32 v119, v0
	v_mov_b32_e32 v120, v0
	v_mov_b32_e32 v121, v0
	v_mov_b32_e32 v122, v0
	v_mov_b32_e32 v123, v0
	v_mov_b32_e32 v124, v0
	v_mov_b32_e32 v125, v0
	v_mov_b32_e32 v126, v0
	v_mov_b32_e32 v127, v0
	v_mov_b32_e32 v92, v0
	v_mov_b32_e32 v93, v0
	v_mov_b32_e32 v94, v0
	v_mov_b32_e32 v95, v0
	v_mov_b32_e32 v96, v0
	v_mov_b32_e32 v97, v0
	v_mov_b32_e32 v98, v0
	v_mov_b32_e32 v99, v0
	v_mov_b32_e32 v100, v0
	v_mov_b32_e32 v101, v0
	v_mov_b32_e32 v102, v0
	v_mov_b32_e32 v103, v0
	v_mov_b32_e32 v104, v0
	v_mov_b32_e32 v105, v0
	v_mov_b32_e32 v106, v0
	v_mov_b32_e32 v107, v0
	v_mov_b32_e32 v128, v0
	v_mov_b32_e32 v129, v0
	v_mov_b32_e32 v130, v0
	v_mov_b32_e32 v131, v0
	v_mov_b32_e32 v132, v0
	v_mov_b32_e32 v133, v0
	v_mov_b32_e32 v134, v0
	v_mov_b32_e32 v135, v0
	v_mov_b32_e32 v136, v0
	v_mov_b32_e32 v137, v0
	v_mov_b32_e32 v138, v0
	v_mov_b32_e32 v139, v0
	v_mov_b32_e32 v140, v0
	v_mov_b32_e32 v141, v0
	v_mov_b32_e32 v142, v0
	v_mov_b32_e32 v143, v0
	.p2align 6
